# gate epilogue: packed f32 mul/add in the sigmoid blocks, redundant cndmask removed
# baseline (speedup 1.0000x reference)
; __device__ __forceinline__ float sigmoidf_(float x) { return __builtin_amdgcn_rcpf(1.f + fexp(-x)); }
; __device__ __forceinline__ void gemm_epi(const Params& p, int l, int kind, const GUnit& u, f32x4 (&acc)[2][2][4][2]) {
;     ...
;     } else {
; #pragma unroll
;       for (int ai = 0; ai < 2; ++ai) {
;         uint4 g[2][4], mm[2][4];
; #pragma unroll
;         for (int bj = 0; bj < 2; ++bj)
; #pragma unroll
;           for (int m = 0; m < 4; ++m) {
;             const int q = (ai * 2 + bj) * 4 + m;
;             g[bj][m] = *reinterpret_cast<const uint4*>((gbu + q * 8192) + lo16);
;             mm[bj][m] = *reinterpret_cast<const uint4*>((mbu + q * 8192) + lo16);
;           }
; #pragma unroll
;         for (int bj = 0; bj < 2; ++bj)
; #pragma unroll
;           for (int m = 0; m < 4; ++m) {
;             const int q = (ai * 2 + bj) * 4 + m;
;             const uint4 yy = g[bj][m]; uint4 mo = mm[bj][m];
;             mo.x = (br > 0) ? mo.x : 0u; mo.y = (br > 0) ? mo.y : 0u; mo.z = (br > 0) ? mo.z : 0u; mo.w = (br > 0) ? mo.w : 0u;
;             f32x4 s0 = acc[ai][bj][m][0], s1 = acc[ai][bj][m][1];
; #pragma unroll
;             for (int j = 0; j < 4; ++j) { s0[j] = sigmoidf_(s0[j]); s1[j] = sigmoidf_(s1[j]); }
.Lal3_a:
	v_mov_b32_e32 v203, v188
	s_lshl_b32 s2, s16, 8
	v_readfirstlane_b32 s15, v203
	s_ashr_i32 s3, s15, 2
	s_andn2_b32 s3, s3, 63
	s_add_i32 s3, s3, s2
	v_and_or_b32 v201, v203, 15, s3
	v_lshlrev_b32_e32 v190, 4, v203
	s_bitcmp0_b32 s17, 0
	s_mov_b64 s[2:3], -1
	s_cbranch_scc1 .LBB0_948
	s_ashr_i32 s2, s17, 1
	s_cmp_gt_i32 s2, 0
	s_cselect_b64 s[10:11], -1, 0
	s_cmp_lg_u32 s2, 0
	s_cbranch_scc1 .Lg3_general
	global_load_dwordx4 v[128:131], v190, s[74:75]
	v_add_u32_e32 v223, 0x2000, v190
	global_load_dwordx4 v[140:143], v223, s[74:75]
	v_add_u32_e32 v236, 0x4000, v190
	global_load_dwordx4 v[156:159], v236, s[74:75]
	v_add_u32_e32 v223, 0x6000, v190
	global_load_dwordx4 v[168:171], v223, s[74:75]
	v_add_u32_e32 v236, 0x8000, v190
	global_load_dwordx4 v[164:167], v236, s[74:75]
	v_add_u32_e32 v223, 0xa000, v190
	global_load_dwordx4 v[152:155], v223, s[74:75]
	v_add_u32_e32 v236, 0xc000, v190
	global_load_dwordx4 v[144:147], v236, s[74:75]
	v_add_u32_e32 v223, 0xe000, v190
	global_load_dwordx4 v[132:135], v223, s[74:75]
	s_mov_b32 s22, 0xbfb8aa3b
	s_mov_b32 s23, 1.0
	v_pk_mul_f32 v[124:125], v[124:125], s[22:23] op_sel_hi:[1,0]
	v_pk_mul_f32 v[126:127], v[126:127], s[22:23] op_sel_hi:[1,0]
	v_pk_mul_f32 v[120:121], v[120:121], s[22:23] op_sel_hi:[1,0]
	v_pk_mul_f32 v[122:123], v[122:123], s[22:23] op_sel_hi:[1,0]
	v_exp_f32_e32 v124, v124
	v_exp_f32_e32 v125, v125
	v_exp_f32_e32 v126, v126
	v_exp_f32_e32 v127, v127
	v_exp_f32_e32 v120, v120
	v_exp_f32_e32 v121, v121
	v_exp_f32_e32 v122, v122
	v_exp_f32_e32 v123, v123
	v_pk_add_f32 v[124:125], v[124:125], s[22:23] op_sel:[0,1] op_sel_hi:[1,1]
	v_pk_add_f32 v[126:127], v[126:127], s[22:23] op_sel:[0,1] op_sel_hi:[1,1]
	v_pk_add_f32 v[120:121], v[120:121], s[22:23] op_sel:[0,1] op_sel_hi:[1,1]
	v_pk_add_f32 v[122:123], v[122:123], s[22:23] op_sel:[0,1] op_sel_hi:[1,1]
	v_rcp_f32_e32 v124, v124
	v_rcp_f32_e32 v125, v125
	v_rcp_f32_e32 v126, v126
	v_rcp_f32_e32 v127, v127
	v_rcp_f32_e32 v120, v120
	v_rcp_f32_e32 v121, v121
	v_rcp_f32_e32 v122, v122
	v_rcp_f32_e32 v123, v123
	v_pk_mul_f32 v[116:117], v[116:117], s[22:23] op_sel_hi:[1,0]
	v_pk_mul_f32 v[118:119], v[118:119], s[22:23] op_sel_hi:[1,0]
	v_pk_mul_f32 v[112:113], v[112:113], s[22:23] op_sel_hi:[1,0]
	v_pk_mul_f32 v[114:115], v[114:115], s[22:23] op_sel_hi:[1,0]
	v_exp_f32_e32 v116, v116
	v_exp_f32_e32 v117, v117
	v_exp_f32_e32 v118, v118
	v_exp_f32_e32 v119, v119
	v_exp_f32_e32 v112, v112
	v_exp_f32_e32 v113, v113
	v_exp_f32_e32 v114, v114
	v_exp_f32_e32 v115, v115
	v_pk_add_f32 v[116:117], v[116:117], s[22:23] op_sel:[0,1] op_sel_hi:[1,1]
	v_pk_add_f32 v[118:119], v[118:119], s[22:23] op_sel:[0,1] op_sel_hi:[1,1]
	v_pk_add_f32 v[112:113], v[112:113], s[22:23] op_sel:[0,1] op_sel_hi:[1,1]
	v_pk_add_f32 v[114:115], v[114:115], s[22:23] op_sel:[0,1] op_sel_hi:[1,1]
	v_rcp_f32_e32 v116, v116
	v_rcp_f32_e32 v117, v117
	v_rcp_f32_e32 v118, v118
	v_rcp_f32_e32 v119, v119
	v_rcp_f32_e32 v112, v112
	v_rcp_f32_e32 v113, v113
	v_rcp_f32_e32 v114, v114
	v_rcp_f32_e32 v115, v115
	v_pk_mul_f32 v[108:109], v[108:109], s[22:23] op_sel_hi:[1,0]
	v_pk_mul_f32 v[110:111], v[110:111], s[22:23] op_sel_hi:[1,0]
	v_pk_mul_f32 v[104:105], v[104:105], s[22:23] op_sel_hi:[1,0]
	v_pk_mul_f32 v[106:107], v[106:107], s[22:23] op_sel_hi:[1,0]
	v_exp_f32_e32 v108, v108
	v_exp_f32_e32 v109, v109
	v_exp_f32_e32 v110, v110
	v_exp_f32_e32 v111, v111
	v_exp_f32_e32 v104, v104
	v_exp_f32_e32 v105, v105
	v_exp_f32_e32 v106, v106
	v_exp_f32_e32 v107, v107
	v_pk_add_f32 v[108:109], v[108:109], s[22:23] op_sel:[0,1] op_sel_hi:[1,1]
	v_pk_add_f32 v[110:111], v[110:111], s[22:23] op_sel:[0,1] op_sel_hi:[1,1]
	v_pk_add_f32 v[104:105], v[104:105], s[22:23] op_sel:[0,1] op_sel_hi:[1,1]
	v_pk_add_f32 v[106:107], v[106:107], s[22:23] op_sel:[0,1] op_sel_hi:[1,1]
	v_rcp_f32_e32 v108, v108
	v_rcp_f32_e32 v109, v109
	v_rcp_f32_e32 v110, v110
	v_rcp_f32_e32 v111, v111
	v_rcp_f32_e32 v104, v104
	v_rcp_f32_e32 v105, v105
	v_rcp_f32_e32 v106, v106
	v_rcp_f32_e32 v107, v107
	v_pk_mul_f32 v[100:101], v[100:101], s[22:23] op_sel_hi:[1,0]
	v_pk_mul_f32 v[102:103], v[102:103], s[22:23] op_sel_hi:[1,0]
	v_pk_mul_f32 v[96:97], v[96:97], s[22:23] op_sel_hi:[1,0]
	v_pk_mul_f32 v[98:99], v[98:99], s[22:23] op_sel_hi:[1,0]
	v_exp_f32_e32 v100, v100
	v_exp_f32_e32 v101, v101
	v_exp_f32_e32 v102, v102
	v_exp_f32_e32 v103, v103
	v_exp_f32_e32 v96, v96
	v_exp_f32_e32 v97, v97
	v_exp_f32_e32 v98, v98
	v_exp_f32_e32 v99, v99
	v_pk_add_f32 v[100:101], v[100:101], s[22:23] op_sel:[0,1] op_sel_hi:[1,1]
	v_pk_add_f32 v[102:103], v[102:103], s[22:23] op_sel:[0,1] op_sel_hi:[1,1]
	v_pk_add_f32 v[96:97], v[96:97], s[22:23] op_sel:[0,1] op_sel_hi:[1,1]
	v_pk_add_f32 v[98:99], v[98:99], s[22:23] op_sel:[0,1] op_sel_hi:[1,1]
	v_rcp_f32_e32 v100, v100
	v_rcp_f32_e32 v101, v101
	v_rcp_f32_e32 v102, v102
	v_rcp_f32_e32 v103, v103
	v_rcp_f32_e32 v96, v96
	v_rcp_f32_e32 v97, v97
	v_rcp_f32_e32 v98, v98
	v_rcp_f32_e32 v99, v99
	v_pk_mul_f32 v[92:93], v[92:93], s[22:23] op_sel_hi:[1,0]
	v_pk_mul_f32 v[94:95], v[94:95], s[22:23] op_sel_hi:[1,0]
	v_pk_mul_f32 v[88:89], v[88:89], s[22:23] op_sel_hi:[1,0]
	v_pk_mul_f32 v[90:91], v[90:91], s[22:23] op_sel_hi:[1,0]
	v_exp_f32_e32 v92, v92
	v_exp_f32_e32 v93, v93
	v_exp_f32_e32 v94, v94
	v_exp_f32_e32 v95, v95
	v_exp_f32_e32 v88, v88
	v_exp_f32_e32 v89, v89
	v_exp_f32_e32 v90, v90
	v_exp_f32_e32 v91, v91
	v_pk_add_f32 v[92:93], v[92:93], s[22:23] op_sel:[0,1] op_sel_hi:[1,1]
	v_pk_add_f32 v[94:95], v[94:95], s[22:23] op_sel:[0,1] op_sel_hi:[1,1]
	v_pk_add_f32 v[88:89], v[88:89], s[22:23] op_sel:[0,1] op_sel_hi:[1,1]
	v_pk_add_f32 v[90:91], v[90:91], s[22:23] op_sel:[0,1] op_sel_hi:[1,1]
; __device__ __forceinline__ float sigmoidf_(float x) { return __builtin_amdgcn_rcpf(1.f + fexp(-x)); }
; __device__ __forceinline__ unsigned pack2(float a, float b) { unsigned r; asm volatile("v_cvt_pk_bf16_f32 %0, %1, %2" : "=v"(r) : "v"(a), "v"(b)); return r; }
; __device__ __forceinline__ void gemm_epi(const Params& p, int l, int kind, const GUnit& u, f32x4 (&acc)[2][2][4][2]) {
;     ...
; #pragma unroll
;         for (int bj = 0; bj < 2; ++bj)
; #pragma unroll
;           for (int m = 0; m < 4; ++m) {
;             const int q = (ai * 2 + bj) * 4 + m;
;             const uint4 yy = g[bj][m]; uint4 mo = mm[bj][m];
;             mo.x = (br > 0) ? mo.x : 0u; mo.y = (br > 0) ? mo.y : 0u; mo.z = (br > 0) ? mo.z : 0u; mo.w = (br > 0) ? mo.w : 0u;
;             f32x4 s0 = acc[ai][bj][m][0], s1 = acc[ai][bj][m][1];
; #pragma unroll
;             for (int j = 0; j < 4; ++j) { s0[j] = sigmoidf_(s0[j]); s1[j] = sigmoidf_(s1[j]); }
;             uint4 o;
;             o.x = pack2(__uint_as_float(yy.x << 16) * s0[0] + __uint_as_float(mo.x << 16), __uint_as_float(yy.x & 0xffff0000u) * s0[1] + __uint_as_float(mo.x & 0xffff0000u));
;             o.y = pack2(__uint_as_float(yy.y << 16) * s0[2] + __uint_as_float(mo.y << 16), __uint_as_float(yy.y & 0xffff0000u) * s0[3] + __uint_as_float(mo.y & 0xffff0000u));
;             o.z = pack2(__uint_as_float(yy.z << 16) * s1[0] + __uint_as_float(mo.z << 16), __uint_as_float(yy.z & 0xffff0000u) * s1[1] + __uint_as_float(mo.z & 0xffff0000u));
;             o.w = pack2(__uint_as_float(yy.w << 16) * s1[2] + __uint_as_float(mo.w << 16), __uint_as_float(yy.w & 0xffff0000u) * s1[3] + __uint_as_float(mo.w & 0xffff0000u));
;             if (br < 2) *reinterpret_cast<uint4*>((mbu + q * 8192) + lo16) = o;
;             mm[bj][m] = o;
;           }
	v_rcp_f32_e32 v92, v92
	v_rcp_f32_e32 v93, v93
	v_rcp_f32_e32 v94, v94
	v_rcp_f32_e32 v95, v95
	v_rcp_f32_e32 v88, v88
	v_rcp_f32_e32 v89, v89
	v_rcp_f32_e32 v90, v90
	v_rcp_f32_e32 v91, v91
	v_pk_mul_f32 v[84:85], v[84:85], s[22:23] op_sel_hi:[1,0]
	v_pk_mul_f32 v[86:87], v[86:87], s[22:23] op_sel_hi:[1,0]
	v_pk_mul_f32 v[80:81], v[80:81], s[22:23] op_sel_hi:[1,0]
	v_pk_mul_f32 v[82:83], v[82:83], s[22:23] op_sel_hi:[1,0]
	v_exp_f32_e32 v84, v84
	v_exp_f32_e32 v85, v85
	v_exp_f32_e32 v86, v86
	v_exp_f32_e32 v87, v87
	v_exp_f32_e32 v80, v80
	v_exp_f32_e32 v81, v81
	v_exp_f32_e32 v82, v82
	v_exp_f32_e32 v83, v83
	v_pk_add_f32 v[84:85], v[84:85], s[22:23] op_sel:[0,1] op_sel_hi:[1,1]
	v_pk_add_f32 v[86:87], v[86:87], s[22:23] op_sel:[0,1] op_sel_hi:[1,1]
	v_pk_add_f32 v[80:81], v[80:81], s[22:23] op_sel:[0,1] op_sel_hi:[1,1]
	v_pk_add_f32 v[82:83], v[82:83], s[22:23] op_sel:[0,1] op_sel_hi:[1,1]
	v_rcp_f32_e32 v84, v84
	v_rcp_f32_e32 v85, v85
	v_rcp_f32_e32 v86, v86
	v_rcp_f32_e32 v87, v87
	v_rcp_f32_e32 v80, v80
	v_rcp_f32_e32 v81, v81
	v_rcp_f32_e32 v82, v82
	v_rcp_f32_e32 v83, v83
	v_pk_mul_f32 v[76:77], v[76:77], s[22:23] op_sel_hi:[1,0]
	v_pk_mul_f32 v[78:79], v[78:79], s[22:23] op_sel_hi:[1,0]
	v_pk_mul_f32 v[72:73], v[72:73], s[22:23] op_sel_hi:[1,0]
	v_pk_mul_f32 v[74:75], v[74:75], s[22:23] op_sel_hi:[1,0]
	v_exp_f32_e32 v76, v76
	v_exp_f32_e32 v77, v77
	v_exp_f32_e32 v78, v78
	v_exp_f32_e32 v79, v79
	v_exp_f32_e32 v72, v72
	v_exp_f32_e32 v73, v73
	v_exp_f32_e32 v74, v74
	v_exp_f32_e32 v75, v75
	v_pk_add_f32 v[76:77], v[76:77], s[22:23] op_sel:[0,1] op_sel_hi:[1,1]
	v_pk_add_f32 v[78:79], v[78:79], s[22:23] op_sel:[0,1] op_sel_hi:[1,1]
	v_pk_add_f32 v[72:73], v[72:73], s[22:23] op_sel:[0,1] op_sel_hi:[1,1]
	v_pk_add_f32 v[74:75], v[74:75], s[22:23] op_sel:[0,1] op_sel_hi:[1,1]
	v_rcp_f32_e32 v76, v76
	v_rcp_f32_e32 v77, v77
	v_rcp_f32_e32 v78, v78
	v_rcp_f32_e32 v79, v79
	v_rcp_f32_e32 v72, v72
	v_rcp_f32_e32 v73, v73
	v_rcp_f32_e32 v74, v74
	v_rcp_f32_e32 v75, v75
	v_pk_mul_f32 v[68:69], v[68:69], s[22:23] op_sel_hi:[1,0]
	v_pk_mul_f32 v[70:71], v[70:71], s[22:23] op_sel_hi:[1,0]
	v_pk_mul_f32 v[64:65], v[64:65], s[22:23] op_sel_hi:[1,0]
	v_pk_mul_f32 v[66:67], v[66:67], s[22:23] op_sel_hi:[1,0]
	v_exp_f32_e32 v68, v68
	v_exp_f32_e32 v69, v69
	v_exp_f32_e32 v70, v70
	v_exp_f32_e32 v71, v71
	v_exp_f32_e32 v64, v64
	v_exp_f32_e32 v65, v65
	v_exp_f32_e32 v66, v66
	v_exp_f32_e32 v67, v67
	v_pk_add_f32 v[68:69], v[68:69], s[22:23] op_sel:[0,1] op_sel_hi:[1,1]
	v_pk_add_f32 v[70:71], v[70:71], s[22:23] op_sel:[0,1] op_sel_hi:[1,1]
	v_pk_add_f32 v[64:65], v[64:65], s[22:23] op_sel:[0,1] op_sel_hi:[1,1]
	v_pk_add_f32 v[66:67], v[66:67], s[22:23] op_sel:[0,1] op_sel_hi:[1,1]
	v_rcp_f32_e32 v68, v68
	v_rcp_f32_e32 v69, v69
	v_rcp_f32_e32 v70, v70
	v_rcp_f32_e32 v71, v71
	v_rcp_f32_e32 v64, v64
	v_rcp_f32_e32 v65, v65
	v_rcp_f32_e32 v66, v66
	v_rcp_f32_e32 v67, v67
	s_waitcnt vmcnt(7)
	v_lshlrev_b32_e32 v228, 16, v128
	v_lshlrev_b32_e32 v229, 16, v129
	v_lshlrev_b32_e32 v230, 16, v130
	v_lshlrev_b32_e32 v231, 16, v131
	v_and_b32_e32 v128, 0xffff0000, v128
	v_and_b32_e32 v129, 0xffff0000, v129
	v_and_b32_e32 v130, 0xffff0000, v130
	v_and_b32_e32 v131, 0xffff0000, v131
	v_fma_f32 v232, v124, v228, 0
	v_fma_f32 v233, v126, v229, 0
	v_fma_f32 v234, v120, v230, 0
	v_fma_f32 v235, v122, v231, 0
	v_fma_f32 v228, v125, v128, 0
	v_fma_f32 v229, v127, v129, 0
	v_fma_f32 v230, v121, v130, 0
	v_fma_f32 v231, v123, v131, 0
	v_cvt_pk_bf16_f32 v128, v232, v228
	v_cvt_pk_bf16_f32 v129, v233, v229
	v_cvt_pk_bf16_f32 v130, v234, v230
	v_cvt_pk_bf16_f32 v131, v235, v231
	v_add_u32_e32 v236, 0x10000, v190
	global_load_dwordx4 v[124:127], v236, s[74:75]
	s_waitcnt vmcnt(7)
	v_lshlrev_b32_e32 v228, 16, v140
	v_lshlrev_b32_e32 v229, 16, v141
	v_lshlrev_b32_e32 v230, 16, v142
	v_lshlrev_b32_e32 v231, 16, v143
	v_and_b32_e32 v140, 0xffff0000, v140
	v_and_b32_e32 v141, 0xffff0000, v141
	v_and_b32_e32 v142, 0xffff0000, v142
	v_and_b32_e32 v143, 0xffff0000, v143
	v_fma_f32 v232, v116, v228, 0
	v_fma_f32 v233, v118, v229, 0
	v_fma_f32 v234, v112, v230, 0
	v_fma_f32 v235, v114, v231, 0
	v_fma_f32 v228, v117, v140, 0
	v_fma_f32 v229, v119, v141, 0
	v_fma_f32 v230, v113, v142, 0
	v_fma_f32 v231, v115, v143, 0
	v_cvt_pk_bf16_f32 v140, v232, v228
	v_cvt_pk_bf16_f32 v141, v233, v229
	v_cvt_pk_bf16_f32 v142, v234, v230
	v_cvt_pk_bf16_f32 v143, v235, v231
	v_add_u32_e32 v223, 0x12000, v190
	global_load_dwordx4 v[116:119], v223, s[74:75]
	s_waitcnt vmcnt(7)
	v_lshlrev_b32_e32 v228, 16, v156
	v_lshlrev_b32_e32 v229, 16, v157
	v_lshlrev_b32_e32 v230, 16, v158
	v_lshlrev_b32_e32 v231, 16, v159
	v_and_b32_e32 v156, 0xffff0000, v156
	v_and_b32_e32 v157, 0xffff0000, v157
	v_and_b32_e32 v158, 0xffff0000, v158
	v_and_b32_e32 v159, 0xffff0000, v159
	v_fma_f32 v232, v108, v228, 0
	v_fma_f32 v233, v110, v229, 0
	v_fma_f32 v234, v104, v230, 0
	v_fma_f32 v235, v106, v231, 0
	v_fma_f32 v228, v109, v156, 0
	v_fma_f32 v229, v111, v157, 0
	v_fma_f32 v230, v105, v158, 0
	v_fma_f32 v231, v107, v159, 0
	v_cvt_pk_bf16_f32 v156, v232, v228
	v_cvt_pk_bf16_f32 v157, v233, v229
	v_cvt_pk_bf16_f32 v158, v234, v230
	v_cvt_pk_bf16_f32 v159, v235, v231
	v_add_u32_e32 v236, 0x14000, v190
	global_load_dwordx4 v[108:111], v236, s[74:75]
	s_waitcnt vmcnt(7)
; __device__ __forceinline__ float sigmoidf_(float x) { return __builtin_amdgcn_rcpf(1.f + fexp(-x)); }
; __device__ __forceinline__ unsigned pack2(float a, float b) { unsigned r; asm volatile("v_cvt_pk_bf16_f32 %0, %1, %2" : "=v"(r) : "v"(a), "v"(b)); return r; }
; __device__ __forceinline__ void gemm_epi(const Params& p, int l, int kind, const GUnit& u, f32x4 (&acc)[2][2][4][2]) {
;     ...
; #pragma unroll
;         for (int bj = 0; bj < 2; ++bj)
; #pragma unroll
;           for (int m = 0; m < 4; ++m) {
;             const int q = (ai * 2 + bj) * 4 + m;
;             const uint4 yy = g[bj][m]; uint4 mo = mm[bj][m];
;             mo.x = (br > 0) ? mo.x : 0u; mo.y = (br > 0) ? mo.y : 0u; mo.z = (br > 0) ? mo.z : 0u; mo.w = (br > 0) ? mo.w : 0u;
;             f32x4 s0 = acc[ai][bj][m][0], s1 = acc[ai][bj][m][1];
; #pragma unroll
;             for (int j = 0; j < 4; ++j) { s0[j] = sigmoidf_(s0[j]); s1[j] = sigmoidf_(s1[j]); }
;             uint4 o;
;             o.x = pack2(__uint_as_float(yy.x << 16) * s0[0] + __uint_as_float(mo.x << 16), __uint_as_float(yy.x & 0xffff0000u) * s0[1] + __uint_as_float(mo.x & 0xffff0000u));
;             o.y = pack2(__uint_as_float(yy.y << 16) * s0[2] + __uint_as_float(mo.y << 16), __uint_as_float(yy.y & 0xffff0000u) * s0[3] + __uint_as_float(mo.y & 0xffff0000u));
;             o.z = pack2(__uint_as_float(yy.z << 16) * s1[0] + __uint_as_float(mo.z << 16), __uint_as_float(yy.z & 0xffff0000u) * s1[1] + __uint_as_float(mo.z & 0xffff0000u));
;             o.w = pack2(__uint_as_float(yy.w << 16) * s1[2] + __uint_as_float(mo.w << 16), __uint_as_float(yy.w & 0xffff0000u) * s1[3] + __uint_as_float(mo.w & 0xffff0000u));
;             if (br < 2) *reinterpret_cast<uint4*>((mbu + q * 8192) + lo16) = o;
;             mm[bj][m] = o;
;           }
	v_lshlrev_b32_e32 v228, 16, v168
	v_lshlrev_b32_e32 v229, 16, v169
	v_lshlrev_b32_e32 v230, 16, v170
	v_lshlrev_b32_e32 v231, 16, v171
	v_and_b32_e32 v168, 0xffff0000, v168
	v_and_b32_e32 v169, 0xffff0000, v169
	v_and_b32_e32 v170, 0xffff0000, v170
	v_and_b32_e32 v171, 0xffff0000, v171
	v_fma_f32 v232, v100, v228, 0
	v_fma_f32 v233, v102, v229, 0
	v_fma_f32 v234, v96, v230, 0
	v_fma_f32 v235, v98, v231, 0
	v_fma_f32 v228, v101, v168, 0
	v_fma_f32 v229, v103, v169, 0
	v_fma_f32 v230, v97, v170, 0
	v_fma_f32 v231, v99, v171, 0
	v_cvt_pk_bf16_f32 v168, v232, v228
	v_cvt_pk_bf16_f32 v169, v233, v229
	v_cvt_pk_bf16_f32 v170, v234, v230
	v_cvt_pk_bf16_f32 v171, v235, v231
	v_add_u32_e32 v223, 0x16000, v190
	global_load_dwordx4 v[100:103], v223, s[74:75]
	s_waitcnt vmcnt(7)
	v_lshlrev_b32_e32 v228, 16, v164
	v_lshlrev_b32_e32 v229, 16, v165
	v_lshlrev_b32_e32 v230, 16, v166
	v_lshlrev_b32_e32 v231, 16, v167
	v_and_b32_e32 v164, 0xffff0000, v164
	v_and_b32_e32 v165, 0xffff0000, v165
	v_and_b32_e32 v166, 0xffff0000, v166
	v_and_b32_e32 v167, 0xffff0000, v167
	v_fma_f32 v232, v92, v228, 0
	v_fma_f32 v233, v94, v229, 0
	v_fma_f32 v234, v88, v230, 0
	v_fma_f32 v235, v90, v231, 0
	v_fma_f32 v228, v93, v164, 0
	v_fma_f32 v229, v95, v165, 0
	v_fma_f32 v230, v89, v166, 0
	v_fma_f32 v231, v91, v167, 0
	v_cvt_pk_bf16_f32 v164, v232, v228
	v_cvt_pk_bf16_f32 v165, v233, v229
	v_cvt_pk_bf16_f32 v166, v234, v230
	v_cvt_pk_bf16_f32 v167, v235, v231
	v_add_u32_e32 v236, 0x18000, v190
	global_load_dwordx4 v[92:95], v236, s[74:75]
	s_waitcnt vmcnt(7)
	v_lshlrev_b32_e32 v228, 16, v152
	v_lshlrev_b32_e32 v229, 16, v153
	v_lshlrev_b32_e32 v230, 16, v154
	v_lshlrev_b32_e32 v231, 16, v155
	v_and_b32_e32 v152, 0xffff0000, v152
	v_and_b32_e32 v153, 0xffff0000, v153
	v_and_b32_e32 v154, 0xffff0000, v154
	v_and_b32_e32 v155, 0xffff0000, v155
	v_fma_f32 v232, v84, v228, 0
	v_fma_f32 v233, v86, v229, 0
	v_fma_f32 v234, v80, v230, 0
	v_fma_f32 v235, v82, v231, 0
	v_fma_f32 v228, v85, v152, 0
	v_fma_f32 v229, v87, v153, 0
	v_fma_f32 v230, v81, v154, 0
	v_fma_f32 v231, v83, v155, 0
	v_cvt_pk_bf16_f32 v152, v232, v228
	v_cvt_pk_bf16_f32 v153, v233, v229
	v_cvt_pk_bf16_f32 v154, v234, v230
	v_cvt_pk_bf16_f32 v155, v235, v231
	v_add_u32_e32 v223, 0x1a000, v190
	global_load_dwordx4 v[84:87], v223, s[74:75]
	s_waitcnt vmcnt(7)
	v_lshlrev_b32_e32 v228, 16, v144
	v_lshlrev_b32_e32 v229, 16, v145
	v_lshlrev_b32_e32 v230, 16, v146
	v_lshlrev_b32_e32 v231, 16, v147
	v_and_b32_e32 v144, 0xffff0000, v144
	v_and_b32_e32 v145, 0xffff0000, v145
	v_and_b32_e32 v146, 0xffff0000, v146
	v_and_b32_e32 v147, 0xffff0000, v147
	v_fma_f32 v232, v76, v228, 0
	v_fma_f32 v233, v78, v229, 0
	v_fma_f32 v234, v72, v230, 0
	v_fma_f32 v235, v74, v231, 0
	v_fma_f32 v228, v77, v144, 0
	v_fma_f32 v229, v79, v145, 0
	v_fma_f32 v230, v73, v146, 0
	v_fma_f32 v231, v75, v147, 0
	v_cvt_pk_bf16_f32 v144, v232, v228
	v_cvt_pk_bf16_f32 v145, v233, v229
	v_cvt_pk_bf16_f32 v146, v234, v230
	v_cvt_pk_bf16_f32 v147, v235, v231
	v_add_u32_e32 v236, 0x1c000, v190
	global_load_dwordx4 v[76:79], v236, s[74:75]
	s_waitcnt vmcnt(7)
	v_lshlrev_b32_e32 v228, 16, v132
	v_lshlrev_b32_e32 v229, 16, v133
	v_lshlrev_b32_e32 v230, 16, v134
	v_lshlrev_b32_e32 v231, 16, v135
	v_and_b32_e32 v132, 0xffff0000, v132
	v_and_b32_e32 v133, 0xffff0000, v133
	v_and_b32_e32 v134, 0xffff0000, v134
	v_and_b32_e32 v135, 0xffff0000, v135
	v_fma_f32 v232, v68, v228, 0
	v_fma_f32 v233, v70, v229, 0
	v_fma_f32 v234, v64, v230, 0
	v_fma_f32 v235, v66, v231, 0
	v_fma_f32 v228, v69, v132, 0
	v_fma_f32 v229, v71, v133, 0
	v_fma_f32 v230, v65, v134, 0
	v_fma_f32 v231, v67, v135, 0
	v_cvt_pk_bf16_f32 v132, v232, v228
	v_cvt_pk_bf16_f32 v133, v233, v229
	v_cvt_pk_bf16_f32 v134, v234, v230
	v_cvt_pk_bf16_f32 v135, v235, v231
	v_add_u32_e32 v223, 0x1e000, v190
	global_load_dwordx4 v[68:71], v223, s[74:75]
	global_store_dwordx4 v190, v[128:131], s[78:79]
	v_add_u32_e32 v223, 0x2000, v190
	global_store_dwordx4 v223, v[140:143], s[78:79]
	v_add_u32_e32 v236, 0x4000, v190
	global_store_dwordx4 v236, v[156:159], s[78:79]
	v_add_u32_e32 v223, 0x6000, v190
	global_store_dwordx4 v223, v[168:171], s[78:79]
	v_add_u32_e32 v236, 0x8000, v190
	global_store_dwordx4 v236, v[164:167], s[78:79]
	v_add_u32_e32 v223, 0xa000, v190
	global_store_dwordx4 v223, v[152:155], s[78:79]
	v_add_u32_e32 v236, 0xc000, v190
	global_store_dwordx4 v236, v[144:147], s[78:79]
	v_add_u32_e32 v223, 0xe000, v190
	global_store_dwordx4 v223, v[132:135], s[78:79]
	s_mov_b32 s22, 0xbfb8aa3b
	s_mov_b32 s23, 1.0
	v_pk_mul_f32 v[60:61], v[60:61], s[22:23] op_sel_hi:[1,0]
	v_pk_mul_f32 v[62:63], v[62:63], s[22:23] op_sel_hi:[1,0]
	v_pk_mul_f32 v[56:57], v[56:57], s[22:23] op_sel_hi:[1,0]
	v_pk_mul_f32 v[58:59], v[58:59], s[22:23] op_sel_hi:[1,0]
	v_exp_f32_e32 v60, v60
	v_exp_f32_e32 v61, v61
	v_exp_f32_e32 v62, v62
	v_exp_f32_e32 v63, v63
	v_exp_f32_e32 v56, v56
	v_exp_f32_e32 v57, v57
	v_exp_f32_e32 v58, v58
	v_exp_f32_e32 v59, v59
	v_pk_add_f32 v[60:61], v[60:61], s[22:23] op_sel:[0,1] op_sel_hi:[1,1]
	v_pk_add_f32 v[62:63], v[62:63], s[22:23] op_sel:[0,1] op_sel_hi:[1,1]
	v_pk_add_f32 v[56:57], v[56:57], s[22:23] op_sel:[0,1] op_sel_hi:[1,1]
	v_pk_add_f32 v[58:59], v[58:59], s[22:23] op_sel:[0,1] op_sel_hi:[1,1]
	v_rcp_f32_e32 v60, v60
	v_rcp_f32_e32 v61, v61
	v_rcp_f32_e32 v62, v62
	v_rcp_f32_e32 v63, v63
	v_rcp_f32_e32 v56, v56
	v_rcp_f32_e32 v57, v57
	v_rcp_f32_e32 v58, v58
	v_rcp_f32_e32 v59, v59
	v_pk_mul_f32 v[52:53], v[52:53], s[22:23] op_sel_hi:[1,0]
	v_pk_mul_f32 v[54:55], v[54:55], s[22:23] op_sel_hi:[1,0]
	v_pk_mul_f32 v[48:49], v[48:49], s[22:23] op_sel_hi:[1,0]
; __device__ __forceinline__ float sigmoidf_(float x) { return __builtin_amdgcn_rcpf(1.f + fexp(-x)); }
; __device__ __forceinline__ unsigned pack2(float a, float b) { unsigned r; asm volatile("v_cvt_pk_bf16_f32 %0, %1, %2" : "=v"(r) : "v"(a), "v"(b)); return r; }
; __device__ __forceinline__ void gemm_epi(const Params& p, int l, int kind, const GUnit& u, f32x4 (&acc)[2][2][4][2]) {
;     ...
; #pragma unroll
;         for (int bj = 0; bj < 2; ++bj)
; #pragma unroll
;           for (int m = 0; m < 4; ++m) {
;             const int q = (ai * 2 + bj) * 4 + m;
;             const uint4 yy = g[bj][m]; uint4 mo = mm[bj][m];
;             mo.x = (br > 0) ? mo.x : 0u; mo.y = (br > 0) ? mo.y : 0u; mo.z = (br > 0) ? mo.z : 0u; mo.w = (br > 0) ? mo.w : 0u;
;             f32x4 s0 = acc[ai][bj][m][0], s1 = acc[ai][bj][m][1];
; #pragma unroll
;             for (int j = 0; j < 4; ++j) { s0[j] = sigmoidf_(s0[j]); s1[j] = sigmoidf_(s1[j]); }
;             uint4 o;
;             o.x = pack2(__uint_as_float(yy.x << 16) * s0[0] + __uint_as_float(mo.x << 16), __uint_as_float(yy.x & 0xffff0000u) * s0[1] + __uint_as_float(mo.x & 0xffff0000u));
;             o.y = pack2(__uint_as_float(yy.y << 16) * s0[2] + __uint_as_float(mo.y << 16), __uint_as_float(yy.y & 0xffff0000u) * s0[3] + __uint_as_float(mo.y & 0xffff0000u));
;             o.z = pack2(__uint_as_float(yy.z << 16) * s1[0] + __uint_as_float(mo.z << 16), __uint_as_float(yy.z & 0xffff0000u) * s1[1] + __uint_as_float(mo.z & 0xffff0000u));
;             o.w = pack2(__uint_as_float(yy.w << 16) * s1[2] + __uint_as_float(mo.w << 16), __uint_as_float(yy.w & 0xffff0000u) * s1[3] + __uint_as_float(mo.w & 0xffff0000u));
;             if (br < 2) *reinterpret_cast<uint4*>((mbu + q * 8192) + lo16) = o;
;             mm[bj][m] = o;
;           }
	v_pk_mul_f32 v[50:51], v[50:51], s[22:23] op_sel_hi:[1,0]
	v_exp_f32_e32 v52, v52
	v_exp_f32_e32 v53, v53
	v_exp_f32_e32 v54, v54
	v_exp_f32_e32 v55, v55
	v_exp_f32_e32 v48, v48
	v_exp_f32_e32 v49, v49
	v_exp_f32_e32 v50, v50
	v_exp_f32_e32 v51, v51
	v_pk_add_f32 v[52:53], v[52:53], s[22:23] op_sel:[0,1] op_sel_hi:[1,1]
	v_pk_add_f32 v[54:55], v[54:55], s[22:23] op_sel:[0,1] op_sel_hi:[1,1]
	v_pk_add_f32 v[48:49], v[48:49], s[22:23] op_sel:[0,1] op_sel_hi:[1,1]
	v_pk_add_f32 v[50:51], v[50:51], s[22:23] op_sel:[0,1] op_sel_hi:[1,1]
	v_rcp_f32_e32 v52, v52
	v_rcp_f32_e32 v53, v53
	v_rcp_f32_e32 v54, v54
	v_rcp_f32_e32 v55, v55
	v_rcp_f32_e32 v48, v48
	v_rcp_f32_e32 v49, v49
	v_rcp_f32_e32 v50, v50
	v_rcp_f32_e32 v51, v51
	v_pk_mul_f32 v[44:45], v[44:45], s[22:23] op_sel_hi:[1,0]
	v_pk_mul_f32 v[46:47], v[46:47], s[22:23] op_sel_hi:[1,0]
	v_pk_mul_f32 v[40:41], v[40:41], s[22:23] op_sel_hi:[1,0]
	v_pk_mul_f32 v[42:43], v[42:43], s[22:23] op_sel_hi:[1,0]
	v_exp_f32_e32 v44, v44
	v_exp_f32_e32 v45, v45
	v_exp_f32_e32 v46, v46
	v_exp_f32_e32 v47, v47
	v_exp_f32_e32 v40, v40
	v_exp_f32_e32 v41, v41
	v_exp_f32_e32 v42, v42
	v_exp_f32_e32 v43, v43
	v_pk_add_f32 v[44:45], v[44:45], s[22:23] op_sel:[0,1] op_sel_hi:[1,1]
	v_pk_add_f32 v[46:47], v[46:47], s[22:23] op_sel:[0,1] op_sel_hi:[1,1]
	v_pk_add_f32 v[40:41], v[40:41], s[22:23] op_sel:[0,1] op_sel_hi:[1,1]
	v_pk_add_f32 v[42:43], v[42:43], s[22:23] op_sel:[0,1] op_sel_hi:[1,1]
	v_rcp_f32_e32 v44, v44
	v_rcp_f32_e32 v45, v45
	v_rcp_f32_e32 v46, v46
	v_rcp_f32_e32 v47, v47
	v_rcp_f32_e32 v40, v40
	v_rcp_f32_e32 v41, v41
	v_rcp_f32_e32 v42, v42
	v_rcp_f32_e32 v43, v43
	v_pk_mul_f32 v[36:37], v[36:37], s[22:23] op_sel_hi:[1,0]
	v_pk_mul_f32 v[38:39], v[38:39], s[22:23] op_sel_hi:[1,0]
	v_pk_mul_f32 v[32:33], v[32:33], s[22:23] op_sel_hi:[1,0]
	v_pk_mul_f32 v[34:35], v[34:35], s[22:23] op_sel_hi:[1,0]
	v_exp_f32_e32 v36, v36
	v_exp_f32_e32 v37, v37
	v_exp_f32_e32 v38, v38
	v_exp_f32_e32 v39, v39
	v_exp_f32_e32 v32, v32
	v_exp_f32_e32 v33, v33
	v_exp_f32_e32 v34, v34
	v_exp_f32_e32 v35, v35
	v_pk_add_f32 v[36:37], v[36:37], s[22:23] op_sel:[0,1] op_sel_hi:[1,1]
	v_pk_add_f32 v[38:39], v[38:39], s[22:23] op_sel:[0,1] op_sel_hi:[1,1]
	v_pk_add_f32 v[32:33], v[32:33], s[22:23] op_sel:[0,1] op_sel_hi:[1,1]
	v_pk_add_f32 v[34:35], v[34:35], s[22:23] op_sel:[0,1] op_sel_hi:[1,1]
	v_rcp_f32_e32 v36, v36
	v_rcp_f32_e32 v37, v37
	v_rcp_f32_e32 v38, v38
	v_rcp_f32_e32 v39, v39
	v_rcp_f32_e32 v32, v32
	v_rcp_f32_e32 v33, v33
	v_rcp_f32_e32 v34, v34
	v_rcp_f32_e32 v35, v35
	v_pk_mul_f32 v[28:29], v[28:29], s[22:23] op_sel_hi:[1,0]
	v_pk_mul_f32 v[30:31], v[30:31], s[22:23] op_sel_hi:[1,0]
	v_pk_mul_f32 v[24:25], v[24:25], s[22:23] op_sel_hi:[1,0]
	v_pk_mul_f32 v[26:27], v[26:27], s[22:23] op_sel_hi:[1,0]
	v_exp_f32_e32 v28, v28
	v_exp_f32_e32 v29, v29
	v_exp_f32_e32 v30, v30
	v_exp_f32_e32 v31, v31
	v_exp_f32_e32 v24, v24
	v_exp_f32_e32 v25, v25
	v_exp_f32_e32 v26, v26
	v_exp_f32_e32 v27, v27
	v_pk_add_f32 v[28:29], v[28:29], s[22:23] op_sel:[0,1] op_sel_hi:[1,1]
	v_pk_add_f32 v[30:31], v[30:31], s[22:23] op_sel:[0,1] op_sel_hi:[1,1]
	v_pk_add_f32 v[24:25], v[24:25], s[22:23] op_sel:[0,1] op_sel_hi:[1,1]
	v_pk_add_f32 v[26:27], v[26:27], s[22:23] op_sel:[0,1] op_sel_hi:[1,1]
	v_rcp_f32_e32 v28, v28
	v_rcp_f32_e32 v29, v29
	v_rcp_f32_e32 v30, v30
	v_rcp_f32_e32 v31, v31
	v_rcp_f32_e32 v24, v24
	v_rcp_f32_e32 v25, v25
	v_rcp_f32_e32 v26, v26
	v_rcp_f32_e32 v27, v27
	v_pk_mul_f32 v[20:21], v[20:21], s[22:23] op_sel_hi:[1,0]
	v_pk_mul_f32 v[22:23], v[22:23], s[22:23] op_sel_hi:[1,0]
	v_pk_mul_f32 v[16:17], v[16:17], s[22:23] op_sel_hi:[1,0]
	v_pk_mul_f32 v[18:19], v[18:19], s[22:23] op_sel_hi:[1,0]
	v_exp_f32_e32 v20, v20
	v_exp_f32_e32 v21, v21
	v_exp_f32_e32 v22, v22
	v_exp_f32_e32 v23, v23
	v_exp_f32_e32 v16, v16
	v_exp_f32_e32 v17, v17
	v_exp_f32_e32 v18, v18
	v_exp_f32_e32 v19, v19
	v_pk_add_f32 v[20:21], v[20:21], s[22:23] op_sel:[0,1] op_sel_hi:[1,1]
	v_pk_add_f32 v[22:23], v[22:23], s[22:23] op_sel:[0,1] op_sel_hi:[1,1]
	v_pk_add_f32 v[16:17], v[16:17], s[22:23] op_sel:[0,1] op_sel_hi:[1,1]
	v_pk_add_f32 v[18:19], v[18:19], s[22:23] op_sel:[0,1] op_sel_hi:[1,1]
	v_rcp_f32_e32 v20, v20
	v_rcp_f32_e32 v21, v21
	v_rcp_f32_e32 v22, v22
	v_rcp_f32_e32 v23, v23
	v_rcp_f32_e32 v16, v16
	v_rcp_f32_e32 v17, v17
	v_rcp_f32_e32 v18, v18
	v_rcp_f32_e32 v19, v19
	v_pk_mul_f32 v[12:13], v[12:13], s[22:23] op_sel_hi:[1,0]
	v_pk_mul_f32 v[14:15], v[14:15], s[22:23] op_sel_hi:[1,0]
	v_pk_mul_f32 v[8:9], v[8:9], s[22:23] op_sel_hi:[1,0]
	v_pk_mul_f32 v[10:11], v[10:11], s[22:23] op_sel_hi:[1,0]
	v_exp_f32_e32 v12, v12
	v_exp_f32_e32 v13, v13
	v_exp_f32_e32 v14, v14
	v_exp_f32_e32 v15, v15
	v_exp_f32_e32 v8, v8
	v_exp_f32_e32 v9, v9
	v_exp_f32_e32 v10, v10
	v_exp_f32_e32 v11, v11
	v_pk_add_f32 v[12:13], v[12:13], s[22:23] op_sel:[0,1] op_sel_hi:[1,1]
	v_pk_add_f32 v[14:15], v[14:15], s[22:23] op_sel:[0,1] op_sel_hi:[1,1]
	v_pk_add_f32 v[8:9], v[8:9], s[22:23] op_sel:[0,1] op_sel_hi:[1,1]
	v_pk_add_f32 v[10:11], v[10:11], s[22:23] op_sel:[0,1] op_sel_hi:[1,1]
	v_rcp_f32_e32 v12, v12
	v_rcp_f32_e32 v13, v13
	v_rcp_f32_e32 v14, v14
	v_rcp_f32_e32 v15, v15
	v_rcp_f32_e32 v8, v8
	v_rcp_f32_e32 v9, v9
	v_rcp_f32_e32 v10, v10
	v_rcp_f32_e32 v11, v11
	v_pk_mul_f32 v[4:5], v[4:5], s[22:23] op_sel_hi:[1,0]
	v_pk_mul_f32 v[6:7], v[6:7], s[22:23] op_sel_hi:[1,0]
	v_pk_mul_f32 v[0:1], v[0:1], s[22:23] op_sel_hi:[1,0]
	v_pk_mul_f32 v[2:3], v[2:3], s[22:23] op_sel_hi:[1,0]
	v_exp_f32_e32 v4, v4
	v_exp_f32_e32 v5, v5
	v_exp_f32_e32 v6, v6
	v_exp_f32_e32 v7, v7
	v_exp_f32_e32 v0, v0
	v_exp_f32_e32 v1, v1
	v_exp_f32_e32 v2, v2
	v_exp_f32_e32 v3, v3
	v_pk_add_f32 v[4:5], v[4:5], s[22:23] op_sel:[0,1] op_sel_hi:[1,1]
	v_pk_add_f32 v[6:7], v[6:7], s[22:23] op_sel:[0,1] op_sel_hi:[1,1]
	v_pk_add_f32 v[0:1], v[0:1], s[22:23] op_sel:[0,1] op_sel_hi:[1,1]
	v_pk_add_f32 v[2:3], v[2:3], s[22:23] op_sel:[0,1] op_sel_hi:[1,1]
	v_rcp_f32_e32 v4, v4
	v_rcp_f32_e32 v5, v5
	v_rcp_f32_e32 v6, v6
	v_rcp_f32_e32 v7, v7
	v_rcp_f32_e32 v0, v0
	v_rcp_f32_e32 v1, v1
	v_rcp_f32_e32 v2, v2
	v_rcp_f32_e32 v3, v3
	s_waitcnt vmcnt(15)
; __device__ __forceinline__ float sigmoidf_(float x) { return __builtin_amdgcn_rcpf(1.f + fexp(-x)); }
; __device__ __forceinline__ unsigned pack2(float a, float b) { unsigned r; asm volatile("v_cvt_pk_bf16_f32 %0, %1, %2" : "=v"(r) : "v"(a), "v"(b)); return r; }
; __device__ __forceinline__ void gemm_epi(const Params& p, int l, int kind, const GUnit& u, f32x4 (&acc)[2][2][4][2]) {
;     ...
; #pragma unroll
;         for (int bj = 0; bj < 2; ++bj)
; #pragma unroll
;           for (int m = 0; m < 4; ++m) {
;             const int q = (ai * 2 + bj) * 4 + m;
;             const uint4 yy = g[bj][m]; uint4 mo = mm[bj][m];
;             mo.x = (br > 0) ? mo.x : 0u; mo.y = (br > 0) ? mo.y : 0u; mo.z = (br > 0) ? mo.z : 0u; mo.w = (br > 0) ? mo.w : 0u;
;             f32x4 s0 = acc[ai][bj][m][0], s1 = acc[ai][bj][m][1];
; #pragma unroll
;             for (int j = 0; j < 4; ++j) { s0[j] = sigmoidf_(s0[j]); s1[j] = sigmoidf_(s1[j]); }
;             uint4 o;
;             o.x = pack2(__uint_as_float(yy.x << 16) * s0[0] + __uint_as_float(mo.x << 16), __uint_as_float(yy.x & 0xffff0000u) * s0[1] + __uint_as_float(mo.x & 0xffff0000u));
;             o.y = pack2(__uint_as_float(yy.y << 16) * s0[2] + __uint_as_float(mo.y << 16), __uint_as_float(yy.y & 0xffff0000u) * s0[3] + __uint_as_float(mo.y & 0xffff0000u));
;             o.z = pack2(__uint_as_float(yy.z << 16) * s1[0] + __uint_as_float(mo.z << 16), __uint_as_float(yy.z & 0xffff0000u) * s1[1] + __uint_as_float(mo.z & 0xffff0000u));
;             o.w = pack2(__uint_as_float(yy.w << 16) * s1[2] + __uint_as_float(mo.w << 16), __uint_as_float(yy.w & 0xffff0000u) * s1[3] + __uint_as_float(mo.w & 0xffff0000u));
;             if (br < 2) *reinterpret_cast<uint4*>((mbu + q * 8192) + lo16) = o;
;             mm[bj][m] = o;
;           }
	v_lshlrev_b32_e32 v228, 16, v124
	v_lshlrev_b32_e32 v229, 16, v125
	v_lshlrev_b32_e32 v230, 16, v126
	v_lshlrev_b32_e32 v231, 16, v127
	v_and_b32_e32 v124, 0xffff0000, v124
	v_and_b32_e32 v125, 0xffff0000, v125
	v_and_b32_e32 v126, 0xffff0000, v126
	v_and_b32_e32 v127, 0xffff0000, v127
	v_fma_f32 v232, v60, v228, 0
	v_fma_f32 v233, v62, v229, 0
	v_fma_f32 v234, v56, v230, 0
	v_fma_f32 v235, v58, v231, 0
	v_fma_f32 v228, v61, v124, 0
	v_fma_f32 v229, v63, v125, 0
	v_fma_f32 v230, v57, v126, 0
	v_fma_f32 v231, v59, v127, 0
	v_cvt_pk_bf16_f32 v124, v232, v228
	v_cvt_pk_bf16_f32 v125, v233, v229
	v_cvt_pk_bf16_f32 v126, v234, v230
	v_cvt_pk_bf16_f32 v127, v235, v231
	v_add_u32_e32 v236, 0x10000, v190
	global_store_dwordx4 v236, v[124:127], s[78:79]
	s_waitcnt vmcnt(14)
	v_lshlrev_b32_e32 v228, 16, v116
	v_lshlrev_b32_e32 v229, 16, v117
	v_lshlrev_b32_e32 v230, 16, v118
	v_lshlrev_b32_e32 v231, 16, v119
	v_and_b32_e32 v116, 0xffff0000, v116
	v_and_b32_e32 v117, 0xffff0000, v117
	v_and_b32_e32 v118, 0xffff0000, v118
	v_and_b32_e32 v119, 0xffff0000, v119
	v_fma_f32 v232, v52, v228, 0
	v_fma_f32 v233, v54, v229, 0
	v_fma_f32 v234, v48, v230, 0
	v_fma_f32 v235, v50, v231, 0
	v_fma_f32 v228, v53, v116, 0
	v_fma_f32 v229, v55, v117, 0
	v_fma_f32 v230, v49, v118, 0
	v_fma_f32 v231, v51, v119, 0
	v_cvt_pk_bf16_f32 v116, v232, v228
	v_cvt_pk_bf16_f32 v117, v233, v229
	v_cvt_pk_bf16_f32 v118, v234, v230
	v_cvt_pk_bf16_f32 v119, v235, v231
	v_add_u32_e32 v223, 0x12000, v190
	global_store_dwordx4 v223, v[116:119], s[78:79]
	s_waitcnt vmcnt(13)
	v_lshlrev_b32_e32 v228, 16, v108
	v_lshlrev_b32_e32 v229, 16, v109
	v_lshlrev_b32_e32 v230, 16, v110
	v_lshlrev_b32_e32 v231, 16, v111
	v_and_b32_e32 v108, 0xffff0000, v108
	v_and_b32_e32 v109, 0xffff0000, v109
	v_and_b32_e32 v110, 0xffff0000, v110
	v_and_b32_e32 v111, 0xffff0000, v111
	v_fma_f32 v232, v44, v228, 0
	v_fma_f32 v233, v46, v229, 0
	v_fma_f32 v234, v40, v230, 0
	v_fma_f32 v235, v42, v231, 0
	v_fma_f32 v228, v45, v108, 0
	v_fma_f32 v229, v47, v109, 0
	v_fma_f32 v230, v41, v110, 0
	v_fma_f32 v231, v43, v111, 0
	v_cvt_pk_bf16_f32 v108, v232, v228
	v_cvt_pk_bf16_f32 v109, v233, v229
	v_cvt_pk_bf16_f32 v110, v234, v230
	v_cvt_pk_bf16_f32 v111, v235, v231
	v_add_u32_e32 v236, 0x14000, v190
	global_store_dwordx4 v236, v[108:111], s[78:79]
	s_waitcnt vmcnt(12)
	v_lshlrev_b32_e32 v228, 16, v100
	v_lshlrev_b32_e32 v229, 16, v101
	v_lshlrev_b32_e32 v230, 16, v102
	v_lshlrev_b32_e32 v231, 16, v103
	v_and_b32_e32 v100, 0xffff0000, v100
	v_and_b32_e32 v101, 0xffff0000, v101
	v_and_b32_e32 v102, 0xffff0000, v102
	v_and_b32_e32 v103, 0xffff0000, v103
	v_fma_f32 v232, v36, v228, 0
	v_fma_f32 v233, v38, v229, 0
	v_fma_f32 v234, v32, v230, 0
	v_fma_f32 v235, v34, v231, 0
	v_fma_f32 v228, v37, v100, 0
	v_fma_f32 v229, v39, v101, 0
	v_fma_f32 v230, v33, v102, 0
	v_fma_f32 v231, v35, v103, 0
	v_cvt_pk_bf16_f32 v100, v232, v228
	v_cvt_pk_bf16_f32 v101, v233, v229
	v_cvt_pk_bf16_f32 v102, v234, v230
	v_cvt_pk_bf16_f32 v103, v235, v231
	v_add_u32_e32 v223, 0x16000, v190
	global_store_dwordx4 v223, v[100:103], s[78:79]
	s_waitcnt vmcnt(11)
	v_lshlrev_b32_e32 v228, 16, v92
	v_lshlrev_b32_e32 v229, 16, v93
	v_lshlrev_b32_e32 v230, 16, v94
	v_lshlrev_b32_e32 v231, 16, v95
	v_and_b32_e32 v92, 0xffff0000, v92
	v_and_b32_e32 v93, 0xffff0000, v93
	v_and_b32_e32 v94, 0xffff0000, v94
	v_and_b32_e32 v95, 0xffff0000, v95
	v_fma_f32 v232, v28, v228, 0
	v_fma_f32 v233, v30, v229, 0
	v_fma_f32 v234, v24, v230, 0
	v_fma_f32 v235, v26, v231, 0
	v_fma_f32 v228, v29, v92, 0
	v_fma_f32 v229, v31, v93, 0
	v_fma_f32 v230, v25, v94, 0
	v_fma_f32 v231, v27, v95, 0
	v_cvt_pk_bf16_f32 v92, v232, v228
	v_cvt_pk_bf16_f32 v93, v233, v229
	v_cvt_pk_bf16_f32 v94, v234, v230
	v_cvt_pk_bf16_f32 v95, v235, v231
	v_add_u32_e32 v236, 0x18000, v190
	global_store_dwordx4 v236, v[92:95], s[78:79]
	s_waitcnt vmcnt(10)
	v_lshlrev_b32_e32 v228, 16, v84
	v_lshlrev_b32_e32 v229, 16, v85
	v_lshlrev_b32_e32 v230, 16, v86
	v_lshlrev_b32_e32 v231, 16, v87
	v_and_b32_e32 v84, 0xffff0000, v84
	v_and_b32_e32 v85, 0xffff0000, v85
	v_and_b32_e32 v86, 0xffff0000, v86
	v_and_b32_e32 v87, 0xffff0000, v87
	v_fma_f32 v232, v20, v228, 0
	v_fma_f32 v233, v22, v229, 0
	v_fma_f32 v234, v16, v230, 0
	v_fma_f32 v235, v18, v231, 0
	v_fma_f32 v228, v21, v84, 0
	v_fma_f32 v229, v23, v85, 0
	v_fma_f32 v230, v17, v86, 0
	v_fma_f32 v231, v19, v87, 0
	v_cvt_pk_bf16_f32 v84, v232, v228
	v_cvt_pk_bf16_f32 v85, v233, v229
	v_cvt_pk_bf16_f32 v86, v234, v230
	v_cvt_pk_bf16_f32 v87, v235, v231
	v_add_u32_e32 v223, 0x1a000, v190
	global_store_dwordx4 v223, v[84:87], s[78:79]
	s_waitcnt vmcnt(9)
	v_lshlrev_b32_e32 v228, 16, v76
	v_lshlrev_b32_e32 v229, 16, v77
	v_lshlrev_b32_e32 v230, 16, v78
	v_lshlrev_b32_e32 v231, 16, v79
	v_and_b32_e32 v76, 0xffff0000, v76
	v_and_b32_e32 v77, 0xffff0000, v77
	v_and_b32_e32 v78, 0xffff0000, v78
	v_and_b32_e32 v79, 0xffff0000, v79
	v_fma_f32 v232, v12, v228, 0
	v_fma_f32 v233, v14, v229, 0
	v_fma_f32 v234, v8, v230, 0
	v_fma_f32 v235, v10, v231, 0
	v_fma_f32 v228, v13, v76, 0
	v_fma_f32 v229, v15, v77, 0
	v_fma_f32 v230, v9, v78, 0
	v_fma_f32 v231, v11, v79, 0
	v_cvt_pk_bf16_f32 v76, v232, v228
	v_cvt_pk_bf16_f32 v77, v233, v229
	v_cvt_pk_bf16_f32 v78, v234, v230
	v_cvt_pk_bf16_f32 v79, v235, v231
	v_add_u32_e32 v236, 0x1c000, v190
	global_store_dwordx4 v236, v[76:79], s[78:79]
	s_waitcnt vmcnt(8)
	v_lshlrev_b32_e32 v228, 16, v68
	v_lshlrev_b32_e32 v229, 16, v69
	v_lshlrev_b32_e32 v230, 16, v70
	v_lshlrev_b32_e32 v231, 16, v71
	v_and_b32_e32 v68, 0xffff0000, v68
	v_and_b32_e32 v69, 0xffff0000, v69
	v_and_b32_e32 v70, 0xffff0000, v70
	v_and_b32_e32 v71, 0xffff0000, v71
	v_fma_f32 v232, v4, v228, 0
	v_fma_f32 v233, v6, v229, 0
	v_fma_f32 v234, v0, v230, 0
	v_fma_f32 v235, v2, v231, 0
	v_fma_f32 v228, v5, v68, 0
	v_fma_f32 v229, v7, v69, 0
	v_fma_f32 v230, v1, v70, 0
	v_fma_f32 v231, v3, v71, 0
	v_cvt_pk_bf16_f32 v68, v232, v228
	v_cvt_pk_bf16_f32 v69, v233, v229
	v_cvt_pk_bf16_f32 v70, v234, v230
	v_cvt_pk_bf16_f32 v71, v235, v231
	v_add_u32_e32 v223, 0x1e000, v190
	global_store_dwordx4 v223, v[68:71], s[78:79]
	s_branch .Lg3_end
; __device__ __forceinline__ float sigmoidf_(float x) { return __builtin_amdgcn_rcpf(1.f + fexp(-x)); }
; __device__ __forceinline__ void gemm_epi(const Params& p, int l, int kind, const GUnit& u, f32x4 (&acc)[2][2][4][2]) {
;     ...
;       for (int ai = 0; ai < 2; ++ai) {
;         uint4 g[2][4], mm[2][4];
; #pragma unroll
;         for (int bj = 0; bj < 2; ++bj)
; #pragma unroll
;           for (int m = 0; m < 4; ++m) {
;             const int q = (ai * 2 + bj) * 4 + m;
;             g[bj][m] = *reinterpret_cast<const uint4*>((gbu + q * 8192) + lo16);
;             mm[bj][m] = *reinterpret_cast<const uint4*>((mbu + q * 8192) + lo16);
;           }
; #pragma unroll
;         for (int bj = 0; bj < 2; ++bj)
; #pragma unroll
;           for (int m = 0; m < 4; ++m) {
;             const int q = (ai * 2 + bj) * 4 + m;
;             const uint4 yy = g[bj][m]; uint4 mo = mm[bj][m];
;             mo.x = (br > 0) ? mo.x : 0u; mo.y = (br > 0) ? mo.y : 0u; mo.z = (br > 0) ? mo.z : 0u; mo.w = (br > 0) ? mo.w : 0u;
;             f32x4 s0 = acc[ai][bj][m][0], s1 = acc[ai][bj][m][1];
; #pragma unroll
;             for (int j = 0; j < 4; ++j) { s0[j] = sigmoidf_(s0[j]); s1[j] = sigmoidf_(s1[j]); }
.Lg3_general:
	global_load_dwordx4 v[128:131], v190, s[74:75]
	global_load_dwordx4 v[224:227], v190, s[78:79]
	v_add_u32_e32 v223, 0x2000, v190
	global_load_dwordx4 v[140:143], v223, s[74:75]
	global_load_dwordx4 v[184:187], v223, s[78:79]
	v_add_u32_e32 v236, 0x4000, v190
	global_load_dwordx4 v[156:159], v236, s[74:75]
	global_load_dwordx4 v[180:183], v236, s[78:79]
	v_add_u32_e32 v223, 0x6000, v190
	global_load_dwordx4 v[168:171], v223, s[74:75]
	global_load_dwordx4 v[176:179], v223, s[78:79]
	v_add_u32_e32 v236, 0x8000, v190
	global_load_dwordx4 v[164:167], v236, s[74:75]
	global_load_dwordx4 v[172:175], v236, s[78:79]
	v_add_u32_e32 v223, 0xa000, v190
	global_load_dwordx4 v[152:155], v223, s[74:75]
	global_load_dwordx4 v[160:163], v223, s[78:79]
	v_add_u32_e32 v236, 0xc000, v190
	global_load_dwordx4 v[144:147], v236, s[74:75]
	global_load_dwordx4 v[148:151], v236, s[78:79]
	v_add_u32_e32 v223, 0xe000, v190
	global_load_dwordx4 v[132:135], v223, s[74:75]
	global_load_dwordx4 v[136:139], v223, s[78:79]
	s_mov_b32 s22, 0xbfb8aa3b
	s_mov_b32 s23, 1.0
	v_pk_mul_f32 v[124:125], v[124:125], s[22:23] op_sel_hi:[1,0]
	v_pk_mul_f32 v[126:127], v[126:127], s[22:23] op_sel_hi:[1,0]
	v_pk_mul_f32 v[120:121], v[120:121], s[22:23] op_sel_hi:[1,0]
	v_pk_mul_f32 v[122:123], v[122:123], s[22:23] op_sel_hi:[1,0]
	v_exp_f32_e32 v124, v124
	v_exp_f32_e32 v125, v125
	v_exp_f32_e32 v126, v126
	v_exp_f32_e32 v127, v127
	v_exp_f32_e32 v120, v120
	v_exp_f32_e32 v121, v121
	v_exp_f32_e32 v122, v122
	v_exp_f32_e32 v123, v123
	v_pk_add_f32 v[124:125], v[124:125], s[22:23] op_sel:[0,1] op_sel_hi:[1,1]
	v_pk_add_f32 v[126:127], v[126:127], s[22:23] op_sel:[0,1] op_sel_hi:[1,1]
	v_pk_add_f32 v[120:121], v[120:121], s[22:23] op_sel:[0,1] op_sel_hi:[1,1]
	v_pk_add_f32 v[122:123], v[122:123], s[22:23] op_sel:[0,1] op_sel_hi:[1,1]
	v_rcp_f32_e32 v124, v124
	v_rcp_f32_e32 v125, v125
	v_rcp_f32_e32 v126, v126
	v_rcp_f32_e32 v127, v127
	v_rcp_f32_e32 v120, v120
	v_rcp_f32_e32 v121, v121
	v_rcp_f32_e32 v122, v122
	v_rcp_f32_e32 v123, v123
	v_pk_mul_f32 v[116:117], v[116:117], s[22:23] op_sel_hi:[1,0]
	v_pk_mul_f32 v[118:119], v[118:119], s[22:23] op_sel_hi:[1,0]
	v_pk_mul_f32 v[112:113], v[112:113], s[22:23] op_sel_hi:[1,0]
	v_pk_mul_f32 v[114:115], v[114:115], s[22:23] op_sel_hi:[1,0]
	v_exp_f32_e32 v116, v116
	v_exp_f32_e32 v117, v117
	v_exp_f32_e32 v118, v118
	v_exp_f32_e32 v119, v119
	v_exp_f32_e32 v112, v112
	v_exp_f32_e32 v113, v113
	v_exp_f32_e32 v114, v114
	v_exp_f32_e32 v115, v115
	v_pk_add_f32 v[116:117], v[116:117], s[22:23] op_sel:[0,1] op_sel_hi:[1,1]
	v_pk_add_f32 v[118:119], v[118:119], s[22:23] op_sel:[0,1] op_sel_hi:[1,1]
	v_pk_add_f32 v[112:113], v[112:113], s[22:23] op_sel:[0,1] op_sel_hi:[1,1]
	v_pk_add_f32 v[114:115], v[114:115], s[22:23] op_sel:[0,1] op_sel_hi:[1,1]
	v_rcp_f32_e32 v116, v116
	v_rcp_f32_e32 v117, v117
	v_rcp_f32_e32 v118, v118
	v_rcp_f32_e32 v119, v119
	v_rcp_f32_e32 v112, v112
	v_rcp_f32_e32 v113, v113
	v_rcp_f32_e32 v114, v114
	v_rcp_f32_e32 v115, v115
	v_pk_mul_f32 v[108:109], v[108:109], s[22:23] op_sel_hi:[1,0]
	v_pk_mul_f32 v[110:111], v[110:111], s[22:23] op_sel_hi:[1,0]
	v_pk_mul_f32 v[104:105], v[104:105], s[22:23] op_sel_hi:[1,0]
	v_pk_mul_f32 v[106:107], v[106:107], s[22:23] op_sel_hi:[1,0]
	v_exp_f32_e32 v108, v108
	v_exp_f32_e32 v109, v109
	v_exp_f32_e32 v110, v110
	v_exp_f32_e32 v111, v111
	v_exp_f32_e32 v104, v104
	v_exp_f32_e32 v105, v105
	v_exp_f32_e32 v106, v106
	v_exp_f32_e32 v107, v107
	v_pk_add_f32 v[108:109], v[108:109], s[22:23] op_sel:[0,1] op_sel_hi:[1,1]
	v_pk_add_f32 v[110:111], v[110:111], s[22:23] op_sel:[0,1] op_sel_hi:[1,1]
	v_pk_add_f32 v[104:105], v[104:105], s[22:23] op_sel:[0,1] op_sel_hi:[1,1]
	v_pk_add_f32 v[106:107], v[106:107], s[22:23] op_sel:[0,1] op_sel_hi:[1,1]
	v_rcp_f32_e32 v108, v108
	v_rcp_f32_e32 v109, v109
	v_rcp_f32_e32 v110, v110
	v_rcp_f32_e32 v111, v111
	v_rcp_f32_e32 v104, v104
	v_rcp_f32_e32 v105, v105
	v_rcp_f32_e32 v106, v106
	v_rcp_f32_e32 v107, v107
	v_pk_mul_f32 v[100:101], v[100:101], s[22:23] op_sel_hi:[1,0]
	v_pk_mul_f32 v[102:103], v[102:103], s[22:23] op_sel_hi:[1,0]
	v_pk_mul_f32 v[96:97], v[96:97], s[22:23] op_sel_hi:[1,0]
	v_pk_mul_f32 v[98:99], v[98:99], s[22:23] op_sel_hi:[1,0]
	v_exp_f32_e32 v100, v100
	v_exp_f32_e32 v101, v101
	v_exp_f32_e32 v102, v102
	v_exp_f32_e32 v103, v103
	v_exp_f32_e32 v96, v96
	v_exp_f32_e32 v97, v97
	v_exp_f32_e32 v98, v98
	v_exp_f32_e32 v99, v99
	v_pk_add_f32 v[100:101], v[100:101], s[22:23] op_sel:[0,1] op_sel_hi:[1,1]
	v_pk_add_f32 v[102:103], v[102:103], s[22:23] op_sel:[0,1] op_sel_hi:[1,1]
	v_pk_add_f32 v[96:97], v[96:97], s[22:23] op_sel:[0,1] op_sel_hi:[1,1]
	v_pk_add_f32 v[98:99], v[98:99], s[22:23] op_sel:[0,1] op_sel_hi:[1,1]
	v_rcp_f32_e32 v100, v100
	v_rcp_f32_e32 v101, v101
	v_rcp_f32_e32 v102, v102
	v_rcp_f32_e32 v103, v103
	v_rcp_f32_e32 v96, v96
	v_rcp_f32_e32 v97, v97
	v_rcp_f32_e32 v98, v98
	v_rcp_f32_e32 v99, v99
	v_pk_mul_f32 v[92:93], v[92:93], s[22:23] op_sel_hi:[1,0]
	v_pk_mul_f32 v[94:95], v[94:95], s[22:23] op_sel_hi:[1,0]
	v_pk_mul_f32 v[88:89], v[88:89], s[22:23] op_sel_hi:[1,0]
	v_pk_mul_f32 v[90:91], v[90:91], s[22:23] op_sel_hi:[1,0]
	v_exp_f32_e32 v92, v92
	v_exp_f32_e32 v93, v93
	v_exp_f32_e32 v94, v94
	v_exp_f32_e32 v95, v95
	v_exp_f32_e32 v88, v88
	v_exp_f32_e32 v89, v89
	v_exp_f32_e32 v90, v90
	v_exp_f32_e32 v91, v91
	v_pk_add_f32 v[92:93], v[92:93], s[22:23] op_sel:[0,1] op_sel_hi:[1,1]
	v_pk_add_f32 v[94:95], v[94:95], s[22:23] op_sel:[0,1] op_sel_hi:[1,1]
	v_pk_add_f32 v[88:89], v[88:89], s[22:23] op_sel:[0,1] op_sel_hi:[1,1]
	v_pk_add_f32 v[90:91], v[90:91], s[22:23] op_sel:[0,1] op_sel_hi:[1,1]
; __device__ __forceinline__ float sigmoidf_(float x) { return __builtin_amdgcn_rcpf(1.f + fexp(-x)); }
; __device__ __forceinline__ unsigned pack2(float a, float b) { unsigned r; asm volatile("v_cvt_pk_bf16_f32 %0, %1, %2" : "=v"(r) : "v"(a), "v"(b)); return r; }
; __device__ __forceinline__ void gemm_epi(const Params& p, int l, int kind, const GUnit& u, f32x4 (&acc)[2][2][4][2]) {
;     ...
;           for (int m = 0; m < 4; ++m) {
;             const int q = (ai * 2 + bj) * 4 + m;
;             const uint4 yy = g[bj][m]; uint4 mo = mm[bj][m];
;             mo.x = (br > 0) ? mo.x : 0u; mo.y = (br > 0) ? mo.y : 0u; mo.z = (br > 0) ? mo.z : 0u; mo.w = (br > 0) ? mo.w : 0u;
;             f32x4 s0 = acc[ai][bj][m][0], s1 = acc[ai][bj][m][1];
; #pragma unroll
;             for (int j = 0; j < 4; ++j) { s0[j] = sigmoidf_(s0[j]); s1[j] = sigmoidf_(s1[j]); }
;             uint4 o;
;             o.x = pack2(__uint_as_float(yy.x << 16) * s0[0] + __uint_as_float(mo.x << 16), __uint_as_float(yy.x & 0xffff0000u) * s0[1] + __uint_as_float(mo.x & 0xffff0000u));
;             o.y = pack2(__uint_as_float(yy.y << 16) * s0[2] + __uint_as_float(mo.y << 16), __uint_as_float(yy.y & 0xffff0000u) * s0[3] + __uint_as_float(mo.y & 0xffff0000u));
;             o.z = pack2(__uint_as_float(yy.z << 16) * s1[0] + __uint_as_float(mo.z << 16), __uint_as_float(yy.z & 0xffff0000u) * s1[1] + __uint_as_float(mo.z & 0xffff0000u));
;             o.w = pack2(__uint_as_float(yy.w << 16) * s1[2] + __uint_as_float(mo.w << 16), __uint_as_float(yy.w & 0xffff0000u) * s1[3] + __uint_as_float(mo.w & 0xffff0000u));
;             if (br < 2) *reinterpret_cast<uint4*>((mbu + q * 8192) + lo16) = o;
	v_rcp_f32_e32 v92, v92
	v_rcp_f32_e32 v93, v93
	v_rcp_f32_e32 v94, v94
	v_rcp_f32_e32 v95, v95
	v_rcp_f32_e32 v88, v88
	v_rcp_f32_e32 v89, v89
	v_rcp_f32_e32 v90, v90
	v_rcp_f32_e32 v91, v91
	v_pk_mul_f32 v[84:85], v[84:85], s[22:23] op_sel_hi:[1,0]
	v_pk_mul_f32 v[86:87], v[86:87], s[22:23] op_sel_hi:[1,0]
	v_pk_mul_f32 v[80:81], v[80:81], s[22:23] op_sel_hi:[1,0]
	v_pk_mul_f32 v[82:83], v[82:83], s[22:23] op_sel_hi:[1,0]
	v_exp_f32_e32 v84, v84
	v_exp_f32_e32 v85, v85
	v_exp_f32_e32 v86, v86
	v_exp_f32_e32 v87, v87
	v_exp_f32_e32 v80, v80
	v_exp_f32_e32 v81, v81
	v_exp_f32_e32 v82, v82
	v_exp_f32_e32 v83, v83
	v_pk_add_f32 v[84:85], v[84:85], s[22:23] op_sel:[0,1] op_sel_hi:[1,1]
	v_pk_add_f32 v[86:87], v[86:87], s[22:23] op_sel:[0,1] op_sel_hi:[1,1]
	v_pk_add_f32 v[80:81], v[80:81], s[22:23] op_sel:[0,1] op_sel_hi:[1,1]
	v_pk_add_f32 v[82:83], v[82:83], s[22:23] op_sel:[0,1] op_sel_hi:[1,1]
	v_rcp_f32_e32 v84, v84
	v_rcp_f32_e32 v85, v85
	v_rcp_f32_e32 v86, v86
	v_rcp_f32_e32 v87, v87
	v_rcp_f32_e32 v80, v80
	v_rcp_f32_e32 v81, v81
	v_rcp_f32_e32 v82, v82
	v_rcp_f32_e32 v83, v83
	v_pk_mul_f32 v[76:77], v[76:77], s[22:23] op_sel_hi:[1,0]
	v_pk_mul_f32 v[78:79], v[78:79], s[22:23] op_sel_hi:[1,0]
	v_pk_mul_f32 v[72:73], v[72:73], s[22:23] op_sel_hi:[1,0]
	v_pk_mul_f32 v[74:75], v[74:75], s[22:23] op_sel_hi:[1,0]
	v_exp_f32_e32 v76, v76
	v_exp_f32_e32 v77, v77
	v_exp_f32_e32 v78, v78
	v_exp_f32_e32 v79, v79
	v_exp_f32_e32 v72, v72
	v_exp_f32_e32 v73, v73
	v_exp_f32_e32 v74, v74
	v_exp_f32_e32 v75, v75
	v_pk_add_f32 v[76:77], v[76:77], s[22:23] op_sel:[0,1] op_sel_hi:[1,1]
	v_pk_add_f32 v[78:79], v[78:79], s[22:23] op_sel:[0,1] op_sel_hi:[1,1]
	v_pk_add_f32 v[72:73], v[72:73], s[22:23] op_sel:[0,1] op_sel_hi:[1,1]
	v_pk_add_f32 v[74:75], v[74:75], s[22:23] op_sel:[0,1] op_sel_hi:[1,1]
	v_rcp_f32_e32 v76, v76
	v_rcp_f32_e32 v77, v77
	v_rcp_f32_e32 v78, v78
	v_rcp_f32_e32 v79, v79
	v_rcp_f32_e32 v72, v72
	v_rcp_f32_e32 v73, v73
	v_rcp_f32_e32 v74, v74
	v_rcp_f32_e32 v75, v75
	v_pk_mul_f32 v[68:69], v[68:69], s[22:23] op_sel_hi:[1,0]
	v_pk_mul_f32 v[70:71], v[70:71], s[22:23] op_sel_hi:[1,0]
	v_pk_mul_f32 v[64:65], v[64:65], s[22:23] op_sel_hi:[1,0]
	v_pk_mul_f32 v[66:67], v[66:67], s[22:23] op_sel_hi:[1,0]
	v_exp_f32_e32 v68, v68
	v_exp_f32_e32 v69, v69
	v_exp_f32_e32 v70, v70
	v_exp_f32_e32 v71, v71
	v_exp_f32_e32 v64, v64
	v_exp_f32_e32 v65, v65
	v_exp_f32_e32 v66, v66
	v_exp_f32_e32 v67, v67
	v_pk_add_f32 v[68:69], v[68:69], s[22:23] op_sel:[0,1] op_sel_hi:[1,1]
	v_pk_add_f32 v[70:71], v[70:71], s[22:23] op_sel:[0,1] op_sel_hi:[1,1]
	v_pk_add_f32 v[64:65], v[64:65], s[22:23] op_sel:[0,1] op_sel_hi:[1,1]
	v_pk_add_f32 v[66:67], v[66:67], s[22:23] op_sel:[0,1] op_sel_hi:[1,1]
	v_rcp_f32_e32 v68, v68
	v_rcp_f32_e32 v69, v69
	v_rcp_f32_e32 v70, v70
	v_rcp_f32_e32 v71, v71
	v_rcp_f32_e32 v64, v64
	v_rcp_f32_e32 v65, v65
	v_rcp_f32_e32 v66, v66
	v_rcp_f32_e32 v67, v67
	s_waitcnt vmcnt(14)
	v_lshlrev_b32_e32 v228, 16, v128
	v_lshlrev_b32_e32 v229, 16, v129
	v_lshlrev_b32_e32 v230, 16, v130
	v_lshlrev_b32_e32 v231, 16, v131
	v_lshlrev_b32_e32 v232, 16, v224
	v_lshlrev_b32_e32 v233, 16, v225
	v_lshlrev_b32_e32 v234, 16, v226
	v_lshlrev_b32_e32 v235, 16, v227
	v_and_b32_e32 v128, 0xffff0000, v128
	v_and_b32_e32 v129, 0xffff0000, v129
	v_and_b32_e32 v130, 0xffff0000, v130
	v_and_b32_e32 v131, 0xffff0000, v131
	v_and_b32_e32 v224, 0xffff0000, v224
	v_and_b32_e32 v225, 0xffff0000, v225
	v_and_b32_e32 v226, 0xffff0000, v226
	v_and_b32_e32 v227, 0xffff0000, v227
	v_fmac_f32_e32 v232, v124, v228
	v_fmac_f32_e32 v233, v126, v229
	v_fmac_f32_e32 v234, v120, v230
	v_fmac_f32_e32 v235, v122, v231
	v_fmac_f32_e32 v224, v125, v128
	v_fmac_f32_e32 v225, v127, v129
	v_fmac_f32_e32 v226, v121, v130
	v_fmac_f32_e32 v227, v123, v131
	v_cvt_pk_bf16_f32 v128, v232, v224
	v_cvt_pk_bf16_f32 v129, v233, v225
	v_cvt_pk_bf16_f32 v130, v234, v226
	v_cvt_pk_bf16_f32 v131, v235, v227
	v_add_u32_e32 v236, 0x10000, v190
	global_load_dwordx4 v[124:127], v236, s[74:75]
	global_load_dwordx4 v[120:123], v236, s[78:79]
	s_waitcnt vmcnt(14)
	v_lshlrev_b32_e32 v228, 16, v140
	v_lshlrev_b32_e32 v229, 16, v141
	v_lshlrev_b32_e32 v230, 16, v142
	v_lshlrev_b32_e32 v231, 16, v143
	v_lshlrev_b32_e32 v232, 16, v184
	v_lshlrev_b32_e32 v233, 16, v185
	v_lshlrev_b32_e32 v234, 16, v186
	v_lshlrev_b32_e32 v235, 16, v187
	v_and_b32_e32 v140, 0xffff0000, v140
	v_and_b32_e32 v141, 0xffff0000, v141
	v_and_b32_e32 v142, 0xffff0000, v142
	v_and_b32_e32 v143, 0xffff0000, v143
	v_and_b32_e32 v184, 0xffff0000, v184
	v_and_b32_e32 v185, 0xffff0000, v185
	v_and_b32_e32 v186, 0xffff0000, v186
	v_and_b32_e32 v187, 0xffff0000, v187
	v_fmac_f32_e32 v232, v116, v228
	v_fmac_f32_e32 v233, v118, v229
	v_fmac_f32_e32 v234, v112, v230
	v_fmac_f32_e32 v235, v114, v231
	v_fmac_f32_e32 v184, v117, v140
	v_fmac_f32_e32 v185, v119, v141
	v_fmac_f32_e32 v186, v113, v142
	v_fmac_f32_e32 v187, v115, v143
	v_cvt_pk_bf16_f32 v140, v232, v184
	v_cvt_pk_bf16_f32 v141, v233, v185
	v_cvt_pk_bf16_f32 v142, v234, v186
	v_cvt_pk_bf16_f32 v143, v235, v187
	v_add_u32_e32 v223, 0x12000, v190
	global_load_dwordx4 v[116:119], v223, s[74:75]
	global_load_dwordx4 v[112:115], v223, s[78:79]
	s_waitcnt vmcnt(14)
; __device__ __forceinline__ float sigmoidf_(float x) { return __builtin_amdgcn_rcpf(1.f + fexp(-x)); }
; __device__ __forceinline__ unsigned pack2(float a, float b) { unsigned r; asm volatile("v_cvt_pk_bf16_f32 %0, %1, %2" : "=v"(r) : "v"(a), "v"(b)); return r; }
; __device__ __forceinline__ void gemm_epi(const Params& p, int l, int kind, const GUnit& u, f32x4 (&acc)[2][2][4][2]) {
;     ...
;           for (int m = 0; m < 4; ++m) {
;             const int q = (ai * 2 + bj) * 4 + m;
;             const uint4 yy = g[bj][m]; uint4 mo = mm[bj][m];
;             mo.x = (br > 0) ? mo.x : 0u; mo.y = (br > 0) ? mo.y : 0u; mo.z = (br > 0) ? mo.z : 0u; mo.w = (br > 0) ? mo.w : 0u;
;             f32x4 s0 = acc[ai][bj][m][0], s1 = acc[ai][bj][m][1];
; #pragma unroll
;             for (int j = 0; j < 4; ++j) { s0[j] = sigmoidf_(s0[j]); s1[j] = sigmoidf_(s1[j]); }
;             uint4 o;
;             o.x = pack2(__uint_as_float(yy.x << 16) * s0[0] + __uint_as_float(mo.x << 16), __uint_as_float(yy.x & 0xffff0000u) * s0[1] + __uint_as_float(mo.x & 0xffff0000u));
;             o.y = pack2(__uint_as_float(yy.y << 16) * s0[2] + __uint_as_float(mo.y << 16), __uint_as_float(yy.y & 0xffff0000u) * s0[3] + __uint_as_float(mo.y & 0xffff0000u));
;             o.z = pack2(__uint_as_float(yy.z << 16) * s1[0] + __uint_as_float(mo.z << 16), __uint_as_float(yy.z & 0xffff0000u) * s1[1] + __uint_as_float(mo.z & 0xffff0000u));
;             o.w = pack2(__uint_as_float(yy.w << 16) * s1[2] + __uint_as_float(mo.w << 16), __uint_as_float(yy.w & 0xffff0000u) * s1[3] + __uint_as_float(mo.w & 0xffff0000u));
;             if (br < 2) *reinterpret_cast<uint4*>((mbu + q * 8192) + lo16) = o;
	v_lshlrev_b32_e32 v228, 16, v156
	v_lshlrev_b32_e32 v229, 16, v157
	v_lshlrev_b32_e32 v230, 16, v158
	v_lshlrev_b32_e32 v231, 16, v159
	v_lshlrev_b32_e32 v232, 16, v180
	v_lshlrev_b32_e32 v233, 16, v181
	v_lshlrev_b32_e32 v234, 16, v182
	v_lshlrev_b32_e32 v235, 16, v183
	v_and_b32_e32 v156, 0xffff0000, v156
	v_and_b32_e32 v157, 0xffff0000, v157
	v_and_b32_e32 v158, 0xffff0000, v158
	v_and_b32_e32 v159, 0xffff0000, v159
	v_and_b32_e32 v180, 0xffff0000, v180
	v_and_b32_e32 v181, 0xffff0000, v181
	v_and_b32_e32 v182, 0xffff0000, v182
	v_and_b32_e32 v183, 0xffff0000, v183
	v_fmac_f32_e32 v232, v108, v228
	v_fmac_f32_e32 v233, v110, v229
	v_fmac_f32_e32 v234, v104, v230
	v_fmac_f32_e32 v235, v106, v231
	v_fmac_f32_e32 v180, v109, v156
	v_fmac_f32_e32 v181, v111, v157
	v_fmac_f32_e32 v182, v105, v158
	v_fmac_f32_e32 v183, v107, v159
	v_cvt_pk_bf16_f32 v156, v232, v180
	v_cvt_pk_bf16_f32 v157, v233, v181
	v_cvt_pk_bf16_f32 v158, v234, v182
	v_cvt_pk_bf16_f32 v159, v235, v183
	v_add_u32_e32 v236, 0x14000, v190
	global_load_dwordx4 v[108:111], v236, s[74:75]
	global_load_dwordx4 v[104:107], v236, s[78:79]
	s_waitcnt vmcnt(14)
	v_lshlrev_b32_e32 v228, 16, v168
	v_lshlrev_b32_e32 v229, 16, v169
	v_lshlrev_b32_e32 v230, 16, v170
	v_lshlrev_b32_e32 v231, 16, v171
	v_lshlrev_b32_e32 v232, 16, v176
	v_lshlrev_b32_e32 v233, 16, v177
	v_lshlrev_b32_e32 v234, 16, v178
	v_lshlrev_b32_e32 v235, 16, v179
	v_and_b32_e32 v168, 0xffff0000, v168
	v_and_b32_e32 v169, 0xffff0000, v169
	v_and_b32_e32 v170, 0xffff0000, v170
	v_and_b32_e32 v171, 0xffff0000, v171
	v_and_b32_e32 v176, 0xffff0000, v176
	v_and_b32_e32 v177, 0xffff0000, v177
	v_and_b32_e32 v178, 0xffff0000, v178
	v_and_b32_e32 v179, 0xffff0000, v179
	v_fmac_f32_e32 v232, v100, v228
	v_fmac_f32_e32 v233, v102, v229
	v_fmac_f32_e32 v234, v96, v230
	v_fmac_f32_e32 v235, v98, v231
	v_fmac_f32_e32 v176, v101, v168
	v_fmac_f32_e32 v177, v103, v169
	v_fmac_f32_e32 v178, v97, v170
	v_fmac_f32_e32 v179, v99, v171
	v_cvt_pk_bf16_f32 v168, v232, v176
	v_cvt_pk_bf16_f32 v169, v233, v177
	v_cvt_pk_bf16_f32 v170, v234, v178
	v_cvt_pk_bf16_f32 v171, v235, v179
	v_add_u32_e32 v223, 0x16000, v190
	global_load_dwordx4 v[100:103], v223, s[74:75]
	global_load_dwordx4 v[96:99], v223, s[78:79]
	s_waitcnt vmcnt(14)
	v_lshlrev_b32_e32 v228, 16, v164
	v_lshlrev_b32_e32 v229, 16, v165
	v_lshlrev_b32_e32 v230, 16, v166
	v_lshlrev_b32_e32 v231, 16, v167
	v_lshlrev_b32_e32 v232, 16, v172
	v_lshlrev_b32_e32 v233, 16, v173
	v_lshlrev_b32_e32 v234, 16, v174
	v_lshlrev_b32_e32 v235, 16, v175
	v_and_b32_e32 v164, 0xffff0000, v164
	v_and_b32_e32 v165, 0xffff0000, v165
	v_and_b32_e32 v166, 0xffff0000, v166
	v_and_b32_e32 v167, 0xffff0000, v167
	v_and_b32_e32 v172, 0xffff0000, v172
	v_and_b32_e32 v173, 0xffff0000, v173
	v_and_b32_e32 v174, 0xffff0000, v174
	v_and_b32_e32 v175, 0xffff0000, v175
	v_fmac_f32_e32 v232, v92, v228
	v_fmac_f32_e32 v233, v94, v229
	v_fmac_f32_e32 v234, v88, v230
	v_fmac_f32_e32 v235, v90, v231
	v_fmac_f32_e32 v172, v93, v164
	v_fmac_f32_e32 v173, v95, v165
	v_fmac_f32_e32 v174, v89, v166
	v_fmac_f32_e32 v175, v91, v167
	v_cvt_pk_bf16_f32 v164, v232, v172
	v_cvt_pk_bf16_f32 v165, v233, v173
	v_cvt_pk_bf16_f32 v166, v234, v174
	v_cvt_pk_bf16_f32 v167, v235, v175
	v_add_u32_e32 v236, 0x18000, v190
	global_load_dwordx4 v[92:95], v236, s[74:75]
	global_load_dwordx4 v[88:91], v236, s[78:79]
	s_waitcnt vmcnt(14)
	v_lshlrev_b32_e32 v228, 16, v152
	v_lshlrev_b32_e32 v229, 16, v153
	v_lshlrev_b32_e32 v230, 16, v154
	v_lshlrev_b32_e32 v231, 16, v155
	v_lshlrev_b32_e32 v232, 16, v160
	v_lshlrev_b32_e32 v233, 16, v161
	v_lshlrev_b32_e32 v234, 16, v162
	v_lshlrev_b32_e32 v235, 16, v163
	v_and_b32_e32 v152, 0xffff0000, v152
	v_and_b32_e32 v153, 0xffff0000, v153
	v_and_b32_e32 v154, 0xffff0000, v154
	v_and_b32_e32 v155, 0xffff0000, v155
	v_and_b32_e32 v160, 0xffff0000, v160
	v_and_b32_e32 v161, 0xffff0000, v161
	v_and_b32_e32 v162, 0xffff0000, v162
	v_and_b32_e32 v163, 0xffff0000, v163
	v_fmac_f32_e32 v232, v84, v228
	v_fmac_f32_e32 v233, v86, v229
	v_fmac_f32_e32 v234, v80, v230
	v_fmac_f32_e32 v235, v82, v231
	v_fmac_f32_e32 v160, v85, v152
	v_fmac_f32_e32 v161, v87, v153
	v_fmac_f32_e32 v162, v81, v154
	v_fmac_f32_e32 v163, v83, v155
	v_cvt_pk_bf16_f32 v152, v232, v160
	v_cvt_pk_bf16_f32 v153, v233, v161
	v_cvt_pk_bf16_f32 v154, v234, v162
	v_cvt_pk_bf16_f32 v155, v235, v163
	v_add_u32_e32 v223, 0x1a000, v190
	global_load_dwordx4 v[84:87], v223, s[74:75]
	global_load_dwordx4 v[80:83], v223, s[78:79]
	s_waitcnt vmcnt(14)
	v_lshlrev_b32_e32 v228, 16, v144
	v_lshlrev_b32_e32 v229, 16, v145
	v_lshlrev_b32_e32 v230, 16, v146
	v_lshlrev_b32_e32 v231, 16, v147
	v_lshlrev_b32_e32 v232, 16, v148
	v_lshlrev_b32_e32 v233, 16, v149
	v_lshlrev_b32_e32 v234, 16, v150
	v_lshlrev_b32_e32 v235, 16, v151
	v_and_b32_e32 v144, 0xffff0000, v144
	v_and_b32_e32 v145, 0xffff0000, v145
	v_and_b32_e32 v146, 0xffff0000, v146
	v_and_b32_e32 v147, 0xffff0000, v147
	v_and_b32_e32 v148, 0xffff0000, v148
	v_and_b32_e32 v149, 0xffff0000, v149
	v_and_b32_e32 v150, 0xffff0000, v150
	v_and_b32_e32 v151, 0xffff0000, v151
	v_fmac_f32_e32 v232, v76, v228
	v_fmac_f32_e32 v233, v78, v229
	v_fmac_f32_e32 v234, v72, v230
	v_fmac_f32_e32 v235, v74, v231
	v_fmac_f32_e32 v148, v77, v144
	v_fmac_f32_e32 v149, v79, v145
	v_fmac_f32_e32 v150, v73, v146
	v_fmac_f32_e32 v151, v75, v147
	v_cvt_pk_bf16_f32 v144, v232, v148
	v_cvt_pk_bf16_f32 v145, v233, v149
	v_cvt_pk_bf16_f32 v146, v234, v150
	v_cvt_pk_bf16_f32 v147, v235, v151
	v_add_u32_e32 v236, 0x1c000, v190
	global_load_dwordx4 v[76:79], v236, s[74:75]
	global_load_dwordx4 v[72:75], v236, s[78:79]
	s_waitcnt vmcnt(14)
	v_lshlrev_b32_e32 v228, 16, v132
	v_lshlrev_b32_e32 v229, 16, v133
	v_lshlrev_b32_e32 v230, 16, v134
	v_lshlrev_b32_e32 v231, 16, v135
	v_lshlrev_b32_e32 v232, 16, v136
	v_lshlrev_b32_e32 v233, 16, v137
	v_lshlrev_b32_e32 v234, 16, v138
	v_lshlrev_b32_e32 v235, 16, v139
	v_and_b32_e32 v132, 0xffff0000, v132
	v_and_b32_e32 v133, 0xffff0000, v133
	v_and_b32_e32 v134, 0xffff0000, v134
	v_and_b32_e32 v135, 0xffff0000, v135
	v_and_b32_e32 v136, 0xffff0000, v136
	v_and_b32_e32 v137, 0xffff0000, v137
	v_and_b32_e32 v138, 0xffff0000, v138
	v_and_b32_e32 v139, 0xffff0000, v139
	v_fmac_f32_e32 v232, v68, v228
	v_fmac_f32_e32 v233, v70, v229
	v_fmac_f32_e32 v234, v64, v230
	v_fmac_f32_e32 v235, v66, v231
	v_fmac_f32_e32 v136, v69, v132
	v_fmac_f32_e32 v137, v71, v133
	v_fmac_f32_e32 v138, v65, v134
	v_fmac_f32_e32 v139, v67, v135
	v_cvt_pk_bf16_f32 v132, v232, v136
	v_cvt_pk_bf16_f32 v133, v233, v137
	v_cvt_pk_bf16_f32 v134, v234, v138
	v_cvt_pk_bf16_f32 v135, v235, v139
	v_add_u32_e32 v223, 0x1e000, v190
	global_load_dwordx4 v[68:71], v223, s[74:75]
	global_load_dwordx4 v[64:67], v223, s[78:79]
	s_cmp_lt_i32 s2, 2
	s_cbranch_scc0 .Lg3_m0
; __device__ __forceinline__ void gemm_epi(const Params& p, int l, int kind, const GUnit& u, f32x4 (&acc)[2][2][4][2]) {
;     ...
;             if (br < 2) *reinterpret_cast<uint4*>((mbu + q * 8192) + lo16) = o;
	global_store_dwordx4 v190, v[128:131], s[78:79]
	v_add_u32_e32 v223, 0x2000, v190
	global_store_dwordx4 v223, v[140:143], s[78:79]
	v_add_u32_e32 v236, 0x4000, v190
	global_store_dwordx4 v236, v[156:159], s[78:79]
	v_add_u32_e32 v223, 0x6000, v190
	global_store_dwordx4 v223, v[168:171], s[78:79]
	v_add_u32_e32 v236, 0x8000, v190
	global_store_dwordx4 v236, v[164:167], s[78:79]
	v_add_u32_e32 v223, 0xa000, v190
	global_store_dwordx4 v223, v[152:155], s[78:79]
	v_add_u32_e32 v236, 0xc000, v190
	global_store_dwordx4 v236, v[144:147], s[78:79]
	v_add_u32_e32 v223, 0xe000, v190
	global_store_dwordx4 v223, v[132:135], s[78:79]
	s_branch .Lg3_s0done

; __device__ __forceinline__ float sigmoidf_(float x) { return __builtin_amdgcn_rcpf(1.f + fexp(-x)); }
; __device__ __forceinline__ void gemm_epi(const Params& p, int l, int kind, const GUnit& u, f32x4 (&acc)[2][2][4][2]) {
;     ...
;       for (int ai = 0; ai < 2; ++ai) {
;         uint4 g[2][4], mm[2][4];
; #pragma unroll
;         for (int bj = 0; bj < 2; ++bj)
; #pragma unroll
;           for (int m = 0; m < 4; ++m) {
;             const int q = (ai * 2 + bj) * 4 + m;
;             g[bj][m] = *reinterpret_cast<const uint4*>((gbu + q * 8192) + lo16);
;             mm[bj][m] = *reinterpret_cast<const uint4*>((mbu + q * 8192) + lo16);
;           }
; #pragma unroll
;         for (int bj = 0; bj < 2; ++bj)
; #pragma unroll
;           for (int m = 0; m < 4; ++m) {
;             const int q = (ai * 2 + bj) * 4 + m;
;             const uint4 yy = g[bj][m]; uint4 mo = mm[bj][m];
;             mo.x = (br > 0) ? mo.x : 0u; mo.y = (br > 0) ? mo.y : 0u; mo.z = (br > 0) ? mo.z : 0u; mo.w = (br > 0) ? mo.w : 0u;
;             f32x4 s0 = acc[ai][bj][m][0], s1 = acc[ai][bj][m][1];
; #pragma unroll
;             for (int j = 0; j < 4; ++j) { s0[j] = sigmoidf_(s0[j]); s1[j] = sigmoidf_(s1[j]); }
.Lg3_s0done:
	s_mov_b32 s22, 0xbfb8aa3b
	s_mov_b32 s23, 1.0
	v_pk_mul_f32 v[60:61], v[60:61], s[22:23] op_sel_hi:[1,0]
	v_pk_mul_f32 v[62:63], v[62:63], s[22:23] op_sel_hi:[1,0]
	v_pk_mul_f32 v[56:57], v[56:57], s[22:23] op_sel_hi:[1,0]
	v_pk_mul_f32 v[58:59], v[58:59], s[22:23] op_sel_hi:[1,0]
	v_exp_f32_e32 v60, v60
	v_exp_f32_e32 v61, v61
	v_exp_f32_e32 v62, v62
	v_exp_f32_e32 v63, v63
	v_exp_f32_e32 v56, v56
	v_exp_f32_e32 v57, v57
	v_exp_f32_e32 v58, v58
	v_exp_f32_e32 v59, v59
	v_pk_add_f32 v[60:61], v[60:61], s[22:23] op_sel:[0,1] op_sel_hi:[1,1]
	v_pk_add_f32 v[62:63], v[62:63], s[22:23] op_sel:[0,1] op_sel_hi:[1,1]
	v_pk_add_f32 v[56:57], v[56:57], s[22:23] op_sel:[0,1] op_sel_hi:[1,1]
	v_pk_add_f32 v[58:59], v[58:59], s[22:23] op_sel:[0,1] op_sel_hi:[1,1]
	v_rcp_f32_e32 v60, v60
	v_rcp_f32_e32 v61, v61
	v_rcp_f32_e32 v62, v62
	v_rcp_f32_e32 v63, v63
	v_rcp_f32_e32 v56, v56
	v_rcp_f32_e32 v57, v57
	v_rcp_f32_e32 v58, v58
	v_rcp_f32_e32 v59, v59
	v_pk_mul_f32 v[52:53], v[52:53], s[22:23] op_sel_hi:[1,0]
	v_pk_mul_f32 v[54:55], v[54:55], s[22:23] op_sel_hi:[1,0]
	v_pk_mul_f32 v[48:49], v[48:49], s[22:23] op_sel_hi:[1,0]
	v_pk_mul_f32 v[50:51], v[50:51], s[22:23] op_sel_hi:[1,0]
	v_exp_f32_e32 v52, v52
	v_exp_f32_e32 v53, v53
	v_exp_f32_e32 v54, v54
	v_exp_f32_e32 v55, v55
	v_exp_f32_e32 v48, v48
	v_exp_f32_e32 v49, v49
	v_exp_f32_e32 v50, v50
	v_exp_f32_e32 v51, v51
	v_pk_add_f32 v[52:53], v[52:53], s[22:23] op_sel:[0,1] op_sel_hi:[1,1]
	v_pk_add_f32 v[54:55], v[54:55], s[22:23] op_sel:[0,1] op_sel_hi:[1,1]
	v_pk_add_f32 v[48:49], v[48:49], s[22:23] op_sel:[0,1] op_sel_hi:[1,1]
	v_pk_add_f32 v[50:51], v[50:51], s[22:23] op_sel:[0,1] op_sel_hi:[1,1]
	v_rcp_f32_e32 v52, v52
	v_rcp_f32_e32 v53, v53
	v_rcp_f32_e32 v54, v54
	v_rcp_f32_e32 v55, v55
	v_rcp_f32_e32 v48, v48
	v_rcp_f32_e32 v49, v49
	v_rcp_f32_e32 v50, v50
	v_rcp_f32_e32 v51, v51
	v_pk_mul_f32 v[44:45], v[44:45], s[22:23] op_sel_hi:[1,0]
	v_pk_mul_f32 v[46:47], v[46:47], s[22:23] op_sel_hi:[1,0]
	v_pk_mul_f32 v[40:41], v[40:41], s[22:23] op_sel_hi:[1,0]
	v_pk_mul_f32 v[42:43], v[42:43], s[22:23] op_sel_hi:[1,0]
	v_exp_f32_e32 v44, v44
	v_exp_f32_e32 v45, v45
	v_exp_f32_e32 v46, v46
	v_exp_f32_e32 v47, v47
	v_exp_f32_e32 v40, v40
	v_exp_f32_e32 v41, v41
	v_exp_f32_e32 v42, v42
	v_exp_f32_e32 v43, v43
	v_pk_add_f32 v[44:45], v[44:45], s[22:23] op_sel:[0,1] op_sel_hi:[1,1]
	v_pk_add_f32 v[46:47], v[46:47], s[22:23] op_sel:[0,1] op_sel_hi:[1,1]
	v_pk_add_f32 v[40:41], v[40:41], s[22:23] op_sel:[0,1] op_sel_hi:[1,1]
	v_pk_add_f32 v[42:43], v[42:43], s[22:23] op_sel:[0,1] op_sel_hi:[1,1]
	v_rcp_f32_e32 v44, v44
	v_rcp_f32_e32 v45, v45
	v_rcp_f32_e32 v46, v46
	v_rcp_f32_e32 v47, v47
	v_rcp_f32_e32 v40, v40
	v_rcp_f32_e32 v41, v41
	v_rcp_f32_e32 v42, v42
	v_rcp_f32_e32 v43, v43
	v_pk_mul_f32 v[36:37], v[36:37], s[22:23] op_sel_hi:[1,0]
	v_pk_mul_f32 v[38:39], v[38:39], s[22:23] op_sel_hi:[1,0]
	v_pk_mul_f32 v[32:33], v[32:33], s[22:23] op_sel_hi:[1,0]
	v_pk_mul_f32 v[34:35], v[34:35], s[22:23] op_sel_hi:[1,0]
	v_exp_f32_e32 v36, v36
	v_exp_f32_e32 v37, v37
	v_exp_f32_e32 v38, v38
	v_exp_f32_e32 v39, v39
	v_exp_f32_e32 v32, v32
	v_exp_f32_e32 v33, v33
	v_exp_f32_e32 v34, v34
	v_exp_f32_e32 v35, v35
	v_pk_add_f32 v[36:37], v[36:37], s[22:23] op_sel:[0,1] op_sel_hi:[1,1]
	v_pk_add_f32 v[38:39], v[38:39], s[22:23] op_sel:[0,1] op_sel_hi:[1,1]
	v_pk_add_f32 v[32:33], v[32:33], s[22:23] op_sel:[0,1] op_sel_hi:[1,1]
	v_pk_add_f32 v[34:35], v[34:35], s[22:23] op_sel:[0,1] op_sel_hi:[1,1]
	v_rcp_f32_e32 v36, v36
	v_rcp_f32_e32 v37, v37
	v_rcp_f32_e32 v38, v38
	v_rcp_f32_e32 v39, v39
	v_rcp_f32_e32 v32, v32
	v_rcp_f32_e32 v33, v33
	v_rcp_f32_e32 v34, v34
	v_rcp_f32_e32 v35, v35
	v_pk_mul_f32 v[28:29], v[28:29], s[22:23] op_sel_hi:[1,0]
	v_pk_mul_f32 v[30:31], v[30:31], s[22:23] op_sel_hi:[1,0]
	v_pk_mul_f32 v[24:25], v[24:25], s[22:23] op_sel_hi:[1,0]
	v_pk_mul_f32 v[26:27], v[26:27], s[22:23] op_sel_hi:[1,0]
	v_exp_f32_e32 v28, v28
	v_exp_f32_e32 v29, v29
	v_exp_f32_e32 v30, v30
	v_exp_f32_e32 v31, v31
	v_exp_f32_e32 v24, v24
	v_exp_f32_e32 v25, v25
	v_exp_f32_e32 v26, v26
	v_exp_f32_e32 v27, v27
	v_pk_add_f32 v[28:29], v[28:29], s[22:23] op_sel:[0,1] op_sel_hi:[1,1]
	v_pk_add_f32 v[30:31], v[30:31], s[22:23] op_sel:[0,1] op_sel_hi:[1,1]
	v_pk_add_f32 v[24:25], v[24:25], s[22:23] op_sel:[0,1] op_sel_hi:[1,1]
	v_pk_add_f32 v[26:27], v[26:27], s[22:23] op_sel:[0,1] op_sel_hi:[1,1]
	v_rcp_f32_e32 v28, v28
	v_rcp_f32_e32 v29, v29
	v_rcp_f32_e32 v30, v30
	v_rcp_f32_e32 v31, v31
	v_rcp_f32_e32 v24, v24
	v_rcp_f32_e32 v25, v25
	v_rcp_f32_e32 v26, v26
	v_rcp_f32_e32 v27, v27
	v_pk_mul_f32 v[20:21], v[20:21], s[22:23] op_sel_hi:[1,0]
	v_pk_mul_f32 v[22:23], v[22:23], s[22:23] op_sel_hi:[1,0]
	v_pk_mul_f32 v[16:17], v[16:17], s[22:23] op_sel_hi:[1,0]
	v_pk_mul_f32 v[18:19], v[18:19], s[22:23] op_sel_hi:[1,0]
	v_exp_f32_e32 v20, v20
	v_exp_f32_e32 v21, v21
	v_exp_f32_e32 v22, v22
	v_exp_f32_e32 v23, v23
	v_exp_f32_e32 v16, v16
	v_exp_f32_e32 v17, v17
	v_exp_f32_e32 v18, v18
	v_exp_f32_e32 v19, v19
	v_pk_add_f32 v[20:21], v[20:21], s[22:23] op_sel:[0,1] op_sel_hi:[1,1]
	v_pk_add_f32 v[22:23], v[22:23], s[22:23] op_sel:[0,1] op_sel_hi:[1,1]
	v_pk_add_f32 v[16:17], v[16:17], s[22:23] op_sel:[0,1] op_sel_hi:[1,1]
	v_pk_add_f32 v[18:19], v[18:19], s[22:23] op_sel:[0,1] op_sel_hi:[1,1]
	v_rcp_f32_e32 v20, v20
	v_rcp_f32_e32 v21, v21
	v_rcp_f32_e32 v22, v22
	v_rcp_f32_e32 v23, v23
	v_rcp_f32_e32 v16, v16
	v_rcp_f32_e32 v17, v17
	v_rcp_f32_e32 v18, v18
	v_rcp_f32_e32 v19, v19
	v_pk_mul_f32 v[12:13], v[12:13], s[22:23] op_sel_hi:[1,0]
	v_pk_mul_f32 v[14:15], v[14:15], s[22:23] op_sel_hi:[1,0]
; __device__ __forceinline__ float sigmoidf_(float x) { return __builtin_amdgcn_rcpf(1.f + fexp(-x)); }
; __device__ __forceinline__ unsigned pack2(float a, float b) { unsigned r; asm volatile("v_cvt_pk_bf16_f32 %0, %1, %2" : "=v"(r) : "v"(a), "v"(b)); return r; }
; __device__ __forceinline__ void gemm_epi(const Params& p, int l, int kind, const GUnit& u, f32x4 (&acc)[2][2][4][2]) {
;     ...
;           for (int m = 0; m < 4; ++m) {
;             const int q = (ai * 2 + bj) * 4 + m;
;             const uint4 yy = g[bj][m]; uint4 mo = mm[bj][m];
;             mo.x = (br > 0) ? mo.x : 0u; mo.y = (br > 0) ? mo.y : 0u; mo.z = (br > 0) ? mo.z : 0u; mo.w = (br > 0) ? mo.w : 0u;
;             f32x4 s0 = acc[ai][bj][m][0], s1 = acc[ai][bj][m][1];
; #pragma unroll
;             for (int j = 0; j < 4; ++j) { s0[j] = sigmoidf_(s0[j]); s1[j] = sigmoidf_(s1[j]); }
;             uint4 o;
;             o.x = pack2(__uint_as_float(yy.x << 16) * s0[0] + __uint_as_float(mo.x << 16), __uint_as_float(yy.x & 0xffff0000u) * s0[1] + __uint_as_float(mo.x & 0xffff0000u));
;             o.y = pack2(__uint_as_float(yy.y << 16) * s0[2] + __uint_as_float(mo.y << 16), __uint_as_float(yy.y & 0xffff0000u) * s0[3] + __uint_as_float(mo.y & 0xffff0000u));
;             o.z = pack2(__uint_as_float(yy.z << 16) * s1[0] + __uint_as_float(mo.z << 16), __uint_as_float(yy.z & 0xffff0000u) * s1[1] + __uint_as_float(mo.z & 0xffff0000u));
;             o.w = pack2(__uint_as_float(yy.w << 16) * s1[2] + __uint_as_float(mo.w << 16), __uint_as_float(yy.w & 0xffff0000u) * s1[3] + __uint_as_float(mo.w & 0xffff0000u));
;             if (br < 2) *reinterpret_cast<uint4*>((mbu + q * 8192) + lo16) = o;
	v_pk_mul_f32 v[8:9], v[8:9], s[22:23] op_sel_hi:[1,0]
	v_pk_mul_f32 v[10:11], v[10:11], s[22:23] op_sel_hi:[1,0]
	v_exp_f32_e32 v12, v12
	v_exp_f32_e32 v13, v13
	v_exp_f32_e32 v14, v14
	v_exp_f32_e32 v15, v15
	v_exp_f32_e32 v8, v8
	v_exp_f32_e32 v9, v9
	v_exp_f32_e32 v10, v10
	v_exp_f32_e32 v11, v11
	v_pk_add_f32 v[12:13], v[12:13], s[22:23] op_sel:[0,1] op_sel_hi:[1,1]
	v_pk_add_f32 v[14:15], v[14:15], s[22:23] op_sel:[0,1] op_sel_hi:[1,1]
	v_pk_add_f32 v[8:9], v[8:9], s[22:23] op_sel:[0,1] op_sel_hi:[1,1]
	v_pk_add_f32 v[10:11], v[10:11], s[22:23] op_sel:[0,1] op_sel_hi:[1,1]
	v_rcp_f32_e32 v12, v12
	v_rcp_f32_e32 v13, v13
	v_rcp_f32_e32 v14, v14
	v_rcp_f32_e32 v15, v15
	v_rcp_f32_e32 v8, v8
	v_rcp_f32_e32 v9, v9
	v_rcp_f32_e32 v10, v10
	v_rcp_f32_e32 v11, v11
	v_pk_mul_f32 v[4:5], v[4:5], s[22:23] op_sel_hi:[1,0]
	v_pk_mul_f32 v[6:7], v[6:7], s[22:23] op_sel_hi:[1,0]
	v_pk_mul_f32 v[0:1], v[0:1], s[22:23] op_sel_hi:[1,0]
	v_pk_mul_f32 v[2:3], v[2:3], s[22:23] op_sel_hi:[1,0]
	v_exp_f32_e32 v4, v4
	v_exp_f32_e32 v5, v5
	v_exp_f32_e32 v6, v6
	v_exp_f32_e32 v7, v7
	v_exp_f32_e32 v0, v0
	v_exp_f32_e32 v1, v1
	v_exp_f32_e32 v2, v2
	v_exp_f32_e32 v3, v3
	v_pk_add_f32 v[4:5], v[4:5], s[22:23] op_sel:[0,1] op_sel_hi:[1,1]
	v_pk_add_f32 v[6:7], v[6:7], s[22:23] op_sel:[0,1] op_sel_hi:[1,1]
	v_pk_add_f32 v[0:1], v[0:1], s[22:23] op_sel:[0,1] op_sel_hi:[1,1]
	v_pk_add_f32 v[2:3], v[2:3], s[22:23] op_sel:[0,1] op_sel_hi:[1,1]
	v_rcp_f32_e32 v4, v4
	v_rcp_f32_e32 v5, v5
	v_rcp_f32_e32 v6, v6
	v_rcp_f32_e32 v7, v7
	v_rcp_f32_e32 v0, v0
	v_rcp_f32_e32 v1, v1
	v_rcp_f32_e32 v2, v2
	v_rcp_f32_e32 v3, v3
	s_waitcnt vmcnt(22)
	v_lshlrev_b32_e32 v228, 16, v124
	v_lshlrev_b32_e32 v229, 16, v125
	v_lshlrev_b32_e32 v230, 16, v126
	v_lshlrev_b32_e32 v231, 16, v127
	v_lshlrev_b32_e32 v232, 16, v120
	v_lshlrev_b32_e32 v233, 16, v121
	v_lshlrev_b32_e32 v234, 16, v122
	v_lshlrev_b32_e32 v235, 16, v123
	v_and_b32_e32 v124, 0xffff0000, v124
	v_and_b32_e32 v125, 0xffff0000, v125
	v_and_b32_e32 v126, 0xffff0000, v126
	v_and_b32_e32 v127, 0xffff0000, v127
	v_and_b32_e32 v120, 0xffff0000, v120
	v_and_b32_e32 v121, 0xffff0000, v121
	v_and_b32_e32 v122, 0xffff0000, v122
	v_and_b32_e32 v123, 0xffff0000, v123
	v_fmac_f32_e32 v232, v60, v228
	v_fmac_f32_e32 v233, v62, v229
	v_fmac_f32_e32 v234, v56, v230
	v_fmac_f32_e32 v235, v58, v231
	v_fmac_f32_e32 v120, v61, v124
	v_fmac_f32_e32 v121, v63, v125
	v_fmac_f32_e32 v122, v57, v126
	v_fmac_f32_e32 v123, v59, v127
	v_cvt_pk_bf16_f32 v124, v232, v120
	v_cvt_pk_bf16_f32 v125, v233, v121
	v_cvt_pk_bf16_f32 v126, v234, v122
	v_cvt_pk_bf16_f32 v127, v235, v123
	s_cmp_lt_i32 s2, 2
	s_cbranch_scc0 .Lg3_ns0
	v_add_u32_e32 v236, 0x10000, v190
	global_store_dwordx4 v236, v[124:127], s[78:79]
.Lg3_ns0:
	s_waitcnt vmcnt(20)
	v_lshlrev_b32_e32 v228, 16, v116
	v_lshlrev_b32_e32 v229, 16, v117
	v_lshlrev_b32_e32 v230, 16, v118
	v_lshlrev_b32_e32 v231, 16, v119
	v_lshlrev_b32_e32 v232, 16, v112
	v_lshlrev_b32_e32 v233, 16, v113
	v_lshlrev_b32_e32 v234, 16, v114
	v_lshlrev_b32_e32 v235, 16, v115
	v_and_b32_e32 v116, 0xffff0000, v116
	v_and_b32_e32 v117, 0xffff0000, v117
	v_and_b32_e32 v118, 0xffff0000, v118
	v_and_b32_e32 v119, 0xffff0000, v119
	v_and_b32_e32 v112, 0xffff0000, v112
	v_and_b32_e32 v113, 0xffff0000, v113
	v_and_b32_e32 v114, 0xffff0000, v114
	v_and_b32_e32 v115, 0xffff0000, v115
	v_fmac_f32_e32 v232, v52, v228
	v_fmac_f32_e32 v233, v54, v229
	v_fmac_f32_e32 v234, v48, v230
	v_fmac_f32_e32 v235, v50, v231
	v_fmac_f32_e32 v112, v53, v116
	v_fmac_f32_e32 v113, v55, v117
	v_fmac_f32_e32 v114, v49, v118
	v_fmac_f32_e32 v115, v51, v119
	v_cvt_pk_bf16_f32 v116, v232, v112
	v_cvt_pk_bf16_f32 v117, v233, v113
	v_cvt_pk_bf16_f32 v118, v234, v114
	v_cvt_pk_bf16_f32 v119, v235, v115
	s_cmp_lt_i32 s2, 2
	s_cbranch_scc0 .Lg3_ns1
	v_add_u32_e32 v223, 0x12000, v190
	global_store_dwordx4 v223, v[116:119], s[78:79]
.Lg3_ns1:
	s_waitcnt vmcnt(18)
	v_lshlrev_b32_e32 v228, 16, v108
	v_lshlrev_b32_e32 v229, 16, v109
	v_lshlrev_b32_e32 v230, 16, v110
	v_lshlrev_b32_e32 v231, 16, v111
	v_lshlrev_b32_e32 v232, 16, v104
	v_lshlrev_b32_e32 v233, 16, v105
	v_lshlrev_b32_e32 v234, 16, v106
	v_lshlrev_b32_e32 v235, 16, v107
	v_and_b32_e32 v108, 0xffff0000, v108
	v_and_b32_e32 v109, 0xffff0000, v109
	v_and_b32_e32 v110, 0xffff0000, v110
	v_and_b32_e32 v111, 0xffff0000, v111
	v_and_b32_e32 v104, 0xffff0000, v104
	v_and_b32_e32 v105, 0xffff0000, v105
	v_and_b32_e32 v106, 0xffff0000, v106
	v_and_b32_e32 v107, 0xffff0000, v107
	v_fmac_f32_e32 v232, v44, v228
	v_fmac_f32_e32 v233, v46, v229
	v_fmac_f32_e32 v234, v40, v230
	v_fmac_f32_e32 v235, v42, v231
	v_fmac_f32_e32 v104, v45, v108
	v_fmac_f32_e32 v105, v47, v109
	v_fmac_f32_e32 v106, v41, v110
	v_fmac_f32_e32 v107, v43, v111
	v_cvt_pk_bf16_f32 v108, v232, v104
	v_cvt_pk_bf16_f32 v109, v233, v105
	v_cvt_pk_bf16_f32 v110, v234, v106
	v_cvt_pk_bf16_f32 v111, v235, v107
	s_cmp_lt_i32 s2, 2
	s_cbranch_scc0 .Lg3_ns2
	v_add_u32_e32 v236, 0x14000, v190
	global_store_dwordx4 v236, v[108:111], s[78:79]
; __device__ __forceinline__ float sigmoidf_(float x) { return __builtin_amdgcn_rcpf(1.f + fexp(-x)); }
; __device__ __forceinline__ unsigned pack2(float a, float b) { unsigned r; asm volatile("v_cvt_pk_bf16_f32 %0, %1, %2" : "=v"(r) : "v"(a), "v"(b)); return r; }
; __device__ __forceinline__ void gemm_epi(const Params& p, int l, int kind, const GUnit& u, f32x4 (&acc)[2][2][4][2]) {
;     ...
;           for (int m = 0; m < 4; ++m) {
;             const int q = (ai * 2 + bj) * 4 + m;
;             const uint4 yy = g[bj][m]; uint4 mo = mm[bj][m];
;             mo.x = (br > 0) ? mo.x : 0u; mo.y = (br > 0) ? mo.y : 0u; mo.z = (br > 0) ? mo.z : 0u; mo.w = (br > 0) ? mo.w : 0u;
;             f32x4 s0 = acc[ai][bj][m][0], s1 = acc[ai][bj][m][1];
; #pragma unroll
;             for (int j = 0; j < 4; ++j) { s0[j] = sigmoidf_(s0[j]); s1[j] = sigmoidf_(s1[j]); }
;             uint4 o;
;             o.x = pack2(__uint_as_float(yy.x << 16) * s0[0] + __uint_as_float(mo.x << 16), __uint_as_float(yy.x & 0xffff0000u) * s0[1] + __uint_as_float(mo.x & 0xffff0000u));
;             o.y = pack2(__uint_as_float(yy.y << 16) * s0[2] + __uint_as_float(mo.y << 16), __uint_as_float(yy.y & 0xffff0000u) * s0[3] + __uint_as_float(mo.y & 0xffff0000u));
;             o.z = pack2(__uint_as_float(yy.z << 16) * s1[0] + __uint_as_float(mo.z << 16), __uint_as_float(yy.z & 0xffff0000u) * s1[1] + __uint_as_float(mo.z & 0xffff0000u));
;             o.w = pack2(__uint_as_float(yy.w << 16) * s1[2] + __uint_as_float(mo.w << 16), __uint_as_float(yy.w & 0xffff0000u) * s1[3] + __uint_as_float(mo.w & 0xffff0000u));
;             if (br < 2) *reinterpret_cast<uint4*>((mbu + q * 8192) + lo16) = o;
.Lg3_ns2:
	s_waitcnt vmcnt(16)
	v_lshlrev_b32_e32 v228, 16, v100
	v_lshlrev_b32_e32 v229, 16, v101
	v_lshlrev_b32_e32 v230, 16, v102
	v_lshlrev_b32_e32 v231, 16, v103
	v_lshlrev_b32_e32 v232, 16, v96
	v_lshlrev_b32_e32 v233, 16, v97
	v_lshlrev_b32_e32 v234, 16, v98
	v_lshlrev_b32_e32 v235, 16, v99
	v_and_b32_e32 v100, 0xffff0000, v100
	v_and_b32_e32 v101, 0xffff0000, v101
	v_and_b32_e32 v102, 0xffff0000, v102
	v_and_b32_e32 v103, 0xffff0000, v103
	v_and_b32_e32 v96, 0xffff0000, v96
	v_and_b32_e32 v97, 0xffff0000, v97
	v_and_b32_e32 v98, 0xffff0000, v98
	v_and_b32_e32 v99, 0xffff0000, v99
	v_fmac_f32_e32 v232, v36, v228
	v_fmac_f32_e32 v233, v38, v229
	v_fmac_f32_e32 v234, v32, v230
	v_fmac_f32_e32 v235, v34, v231
	v_fmac_f32_e32 v96, v37, v100
	v_fmac_f32_e32 v97, v39, v101
	v_fmac_f32_e32 v98, v33, v102
	v_fmac_f32_e32 v99, v35, v103
	v_cvt_pk_bf16_f32 v100, v232, v96
	v_cvt_pk_bf16_f32 v101, v233, v97
	v_cvt_pk_bf16_f32 v102, v234, v98
	v_cvt_pk_bf16_f32 v103, v235, v99
	s_cmp_lt_i32 s2, 2
	s_cbranch_scc0 .Lg3_ns3
	v_add_u32_e32 v223, 0x16000, v190
	global_store_dwordx4 v223, v[100:103], s[78:79]
.Lg3_ns3:
	s_waitcnt vmcnt(14)
	v_lshlrev_b32_e32 v228, 16, v92
	v_lshlrev_b32_e32 v229, 16, v93
	v_lshlrev_b32_e32 v230, 16, v94
	v_lshlrev_b32_e32 v231, 16, v95
	v_lshlrev_b32_e32 v232, 16, v88
	v_lshlrev_b32_e32 v233, 16, v89
	v_lshlrev_b32_e32 v234, 16, v90
	v_lshlrev_b32_e32 v235, 16, v91
	v_and_b32_e32 v92, 0xffff0000, v92
	v_and_b32_e32 v93, 0xffff0000, v93
	v_and_b32_e32 v94, 0xffff0000, v94
	v_and_b32_e32 v95, 0xffff0000, v95
	v_and_b32_e32 v88, 0xffff0000, v88
	v_and_b32_e32 v89, 0xffff0000, v89
	v_and_b32_e32 v90, 0xffff0000, v90
	v_and_b32_e32 v91, 0xffff0000, v91
	v_fmac_f32_e32 v232, v28, v228
	v_fmac_f32_e32 v233, v30, v229
	v_fmac_f32_e32 v234, v24, v230
	v_fmac_f32_e32 v235, v26, v231
	v_fmac_f32_e32 v88, v29, v92
	v_fmac_f32_e32 v89, v31, v93
	v_fmac_f32_e32 v90, v25, v94
	v_fmac_f32_e32 v91, v27, v95
	v_cvt_pk_bf16_f32 v92, v232, v88
	v_cvt_pk_bf16_f32 v93, v233, v89
	v_cvt_pk_bf16_f32 v94, v234, v90
	v_cvt_pk_bf16_f32 v95, v235, v91
	s_cmp_lt_i32 s2, 2
	s_cbranch_scc0 .Lg3_ns4
	v_add_u32_e32 v236, 0x18000, v190
	global_store_dwordx4 v236, v[92:95], s[78:79]
.Lg3_ns4:
	s_waitcnt vmcnt(12)
	v_lshlrev_b32_e32 v228, 16, v84
	v_lshlrev_b32_e32 v229, 16, v85
	v_lshlrev_b32_e32 v230, 16, v86
	v_lshlrev_b32_e32 v231, 16, v87
	v_lshlrev_b32_e32 v232, 16, v80
	v_lshlrev_b32_e32 v233, 16, v81
	v_lshlrev_b32_e32 v234, 16, v82
	v_lshlrev_b32_e32 v235, 16, v83
	v_and_b32_e32 v84, 0xffff0000, v84
	v_and_b32_e32 v85, 0xffff0000, v85
	v_and_b32_e32 v86, 0xffff0000, v86
	v_and_b32_e32 v87, 0xffff0000, v87
	v_and_b32_e32 v80, 0xffff0000, v80
	v_and_b32_e32 v81, 0xffff0000, v81
	v_and_b32_e32 v82, 0xffff0000, v82
	v_and_b32_e32 v83, 0xffff0000, v83
	v_fmac_f32_e32 v232, v20, v228
	v_fmac_f32_e32 v233, v22, v229
	v_fmac_f32_e32 v234, v16, v230
	v_fmac_f32_e32 v235, v18, v231
	v_fmac_f32_e32 v80, v21, v84
	v_fmac_f32_e32 v81, v23, v85
	v_fmac_f32_e32 v82, v17, v86
	v_fmac_f32_e32 v83, v19, v87
	v_cvt_pk_bf16_f32 v84, v232, v80
	v_cvt_pk_bf16_f32 v85, v233, v81
	v_cvt_pk_bf16_f32 v86, v234, v82
	v_cvt_pk_bf16_f32 v87, v235, v83
	s_cmp_lt_i32 s2, 2
	s_cbranch_scc0 .Lg3_ns5
	v_add_u32_e32 v223, 0x1a000, v190
	global_store_dwordx4 v223, v[84:87], s[78:79]
.Lg3_ns5:
	s_waitcnt vmcnt(10)
	v_lshlrev_b32_e32 v228, 16, v76
	v_lshlrev_b32_e32 v229, 16, v77
	v_lshlrev_b32_e32 v230, 16, v78
	v_lshlrev_b32_e32 v231, 16, v79
	v_lshlrev_b32_e32 v232, 16, v72
	v_lshlrev_b32_e32 v233, 16, v73
	v_lshlrev_b32_e32 v234, 16, v74
	v_lshlrev_b32_e32 v235, 16, v75
	v_and_b32_e32 v76, 0xffff0000, v76
	v_and_b32_e32 v77, 0xffff0000, v77
	v_and_b32_e32 v78, 0xffff0000, v78
	v_and_b32_e32 v79, 0xffff0000, v79
	v_and_b32_e32 v72, 0xffff0000, v72
	v_and_b32_e32 v73, 0xffff0000, v73
	v_and_b32_e32 v74, 0xffff0000, v74
	v_and_b32_e32 v75, 0xffff0000, v75
	v_fmac_f32_e32 v232, v12, v228
	v_fmac_f32_e32 v233, v14, v229
	v_fmac_f32_e32 v234, v8, v230
	v_fmac_f32_e32 v235, v10, v231
	v_fmac_f32_e32 v72, v13, v76
	v_fmac_f32_e32 v73, v15, v77
	v_fmac_f32_e32 v74, v9, v78
	v_fmac_f32_e32 v75, v11, v79
	v_cvt_pk_bf16_f32 v76, v232, v72
	v_cvt_pk_bf16_f32 v77, v233, v73
	v_cvt_pk_bf16_f32 v78, v234, v74
	v_cvt_pk_bf16_f32 v79, v235, v75
	s_cmp_lt_i32 s2, 2
	s_cbranch_scc0 .Lg3_ns6
	v_add_u32_e32 v236, 0x1c000, v190
	global_store_dwordx4 v236, v[76:79], s[78:79]
.Lg3_ns6:
	s_waitcnt vmcnt(8)
	v_lshlrev_b32_e32 v228, 16, v68
	v_lshlrev_b32_e32 v229, 16, v69
	v_lshlrev_b32_e32 v230, 16, v70
	v_lshlrev_b32_e32 v231, 16, v71
	v_lshlrev_b32_e32 v232, 16, v64
	v_lshlrev_b32_e32 v233, 16, v65
	v_lshlrev_b32_e32 v234, 16, v66
	v_lshlrev_b32_e32 v235, 16, v67
	v_and_b32_e32 v68, 0xffff0000, v68
	v_and_b32_e32 v69, 0xffff0000, v69
	v_and_b32_e32 v70, 0xffff0000, v70
	v_and_b32_e32 v71, 0xffff0000, v71
	v_and_b32_e32 v64, 0xffff0000, v64
	v_and_b32_e32 v65, 0xffff0000, v65
	v_and_b32_e32 v66, 0xffff0000, v66
	v_and_b32_e32 v67, 0xffff0000, v67
	v_fmac_f32_e32 v232, v4, v228
	v_fmac_f32_e32 v233, v6, v229
	v_fmac_f32_e32 v234, v0, v230
	v_fmac_f32_e32 v235, v2, v231
	v_fmac_f32_e32 v64, v5, v68
	v_fmac_f32_e32 v65, v7, v69
	v_fmac_f32_e32 v66, v1, v70
	v_fmac_f32_e32 v67, v3, v71
	v_cvt_pk_bf16_f32 v68, v232, v64
	v_cvt_pk_bf16_f32 v69, v233, v65
	v_cvt_pk_bf16_f32 v70, v234, v66
	v_cvt_pk_bf16_f32 v71, v235, v67
	s_cmp_lt_i32 s2, 2
	s_cbranch_scc0 .Lg3_ns7
	v_add_u32_e32 v223, 0x1e000, v190
	global_store_dwordx4 v223, v[68:71], s[78:79]
